# v082 + GEMM load blocks: the vmcnt(8) and lgkmcnt(0) waits before the opening barrier merged into one s_waitcnt
# speedup vs baseline: 1.0033x; 1.0002x over previous
; #define PG8_STAGE(bufoff, gbase, voff) do { _Pragma("unroll") for (int _i = 0; _i < 2; ++_i) \
;         __builtin_amdgcn_global_load_lds((const gunsigned*)((const gchar*)(gbase) + (voff)[_i]), (LAS unsigned*)(lds + (bufoff) + ldsw + _i * 8192), 16, 0, 0); } while (0)
; #define PG8_LDA(dst, b, h) do { _Pragma("unroll") for (int m = 0; m < 4; ++m) _Pragma("unroll") for (int k = 0; k < 2; ++k) dst[m][k] = *(const LAS bf16x8*)(lds + PG8_SA(b, h) + aoff + m * 2048 + k * 1024); } while (0)
; #define PG8_LDB(dst, b, h) do { _Pragma("unroll") for (int n = 0; n < 2; ++n) _Pragma("unroll") for (int k = 0; k < 2; ++k) dst[n][k] = *(const LAS bf16x8*)(lds + PG8_SB(b, h) + boff + n * 2048 + k * 1024); } while (0)
; #define PG8_MMA(ai, bj, At, Bt) do { __builtin_amdgcn_s_setprio(1); _Pragma("unroll") for (int m = 0; m < 4; ++m) _Pragma("unroll") for (int n = 0; n < 2; ++n) _Pragma("unroll") for (int k = 0; k < 2; ++k) \
;         acc[ai][bj][m][n] = __builtin_amdgcn_mfma_f32_16x16x32_bf16(Bt[n][k], At[m][k], acc[ai][bj][m][n], 0, 0, 0); __builtin_amdgcn_s_setprio(0); } while (0)
; #define PG8_WAIT_V(n) asm volatile("s_waitcnt vmcnt(" #n ")" ::: "memory")
; #define PG8_WAIT_L(n) asm volatile("s_waitcnt lgkmcnt(" #n ")" ::: "memory")
; #define PG8_BAR __builtin_amdgcn_s_barrier()
; #define PG8_SCHED __builtin_amdgcn_sched_barrier(0)
; template <class Epi, class Sched>
; __device__ __forceinline__ void gemm_phase(LAS unsigned char* lds, const int tid, const Gemm g, const Sched& S, const Epi& E) {
;     ...
;             const gchar* a1 = cA + (size_t)(t + 1) * kstep;
;             const gchar* a2 = last ? nA : cA + (size_t)(t + 2) * kstep; const gchar* b2 = last ? nB : cB + (size_t)(t + 2) * kstep;
;             const gchar* a3 = a2 + kstep; const gchar* b3 = b2 + kstep;
;             PG8_LDB(B0, 0, 0); PG8_LDB(B1, 0, 1); PG8_SCHED; PG8_LDA(At, 0, 0); PG8_STAGE(PG8_SA(1, 1), a1 + hstep, voffA);
;             PG8_WAIT_V(8); PG8_WAIT_L(0); PG8_BAR; PG8_MMA(0, 0, At, B0); PG8_MMA(0, 1, At, B1); PG8_BAR; PG8_SCHED;
;             PG8_LDA(At, 0, 1); PG8_STAGE(PG8_SB(0, 0), b2, voffB); PG8_STAGE(PG8_SB(0, 1), b2 + hstep, voffB); PG8_STAGE(PG8_SA(0, 0), a2, voffA);
;             PG8_WAIT_V(8); PG8_WAIT_L(0); PG8_BAR; PG8_MMA(1, 0, At, B0); PG8_MMA(1, 1, At, B1); PG8_BAR; PG8_SCHED;
.LBB0_319:
	s_add_u32 vcc_lo, s10, 0x100
	s_addc_u32 vcc_hi, s11, 0
	s_add_i32 s39, 0, 0x10000
	s_cmp_eq_u32 s29, 40
	s_cselect_b32 s75, s21, vcc_hi
	s_cselect_b32 s74, s20, vcc_lo
	s_cselect_b32 s73, s1, s93
	s_cselect_b32 s72, s0, s31
	s_add_i32 s30, 0, 0x14000
	v_add_u32_e32 v142, s39, v174
	v_add_u32_e32 v168, s30, v174
	ds_read_b128 v[130:133], v142
	ds_read_b128 v[134:137], v142 offset:1024
	ds_read_b128 v[138:141], v142 offset:2048
	ds_read_b128 v[142:145], v142 offset:3072
	ds_read_b128 v[146:149], v168
	ds_read_b128 v[150:153], v168 offset:1024
	ds_read_b128 v[164:167], v168 offset:2048
	ds_read_b128 v[168:171], v168 offset:3072
	s_add_i32 m0, s46, 0xc000
	ds_read_b128 v[192:195], v190
	ds_read_b128 v[204:207], v190 offset:1024
	ds_read_b128 v[208:211], v190 offset:2048
	ds_read_b128 v[212:215], v190 offset:3072
	ds_read_b128 v[216:219], v190 offset:4096
	ds_read_b128 v[220:223], v190 offset:5120
	ds_read_b128 v[224:227], v190 offset:6144
	ds_read_b128 v[242:245], v190 offset:7168
	global_load_lds_dwordx4 v162, s[10:11]
	s_add_i32 m0, s46, 0xe000
	s_nop 0
	global_load_lds_dwordx4 v160, s[10:11]
	s_waitcnt vmcnt(8) lgkmcnt(0)
	s_setprio 1
	s_barrier
	v_mfma_f32_16x16x32_bf16 v[126:129], v[130:133], v[192:195], v[126:129]
	v_mfma_f32_16x16x32_bf16 v[122:125], v[138:141], v[192:195], v[122:125]
	v_mfma_f32_16x16x32_bf16 v[110:113], v[130:133], v[208:211], v[110:113]
	v_mfma_f32_16x16x32_bf16 v[106:109], v[138:141], v[208:211], v[106:109]
	v_mfma_f32_16x16x32_bf16 v[94:97], v[130:133], v[216:219], v[94:97]
	v_mfma_f32_16x16x32_bf16 v[90:93], v[138:141], v[216:219], v[90:93]
	v_mfma_f32_16x16x32_bf16 v[78:81], v[130:133], v[224:227], v[78:81]
	v_mfma_f32_16x16x32_bf16 v[74:77], v[138:141], v[224:227], v[74:77]
	v_mfma_f32_16x16x32_bf16 v[126:129], v[134:137], v[204:207], v[126:129]
	v_mfma_f32_16x16x32_bf16 v[122:125], v[142:145], v[204:207], v[122:125]
	v_mfma_f32_16x16x32_bf16 v[110:113], v[134:137], v[212:215], v[110:113]
	v_mfma_f32_16x16x32_bf16 v[106:109], v[142:145], v[212:215], v[106:109]
	v_mfma_f32_16x16x32_bf16 v[94:97], v[134:137], v[220:223], v[94:97]
	v_mfma_f32_16x16x32_bf16 v[90:93], v[142:145], v[220:223], v[90:93]
	v_mfma_f32_16x16x32_bf16 v[78:81], v[134:137], v[242:245], v[78:81]
	v_mfma_f32_16x16x32_bf16 v[74:77], v[142:145], v[242:245], v[74:77]
	s_setprio 0
	s_setprio 1
	v_mfma_f32_16x16x32_bf16 v[118:121], v[146:149], v[192:195], v[118:121]
	v_mfma_f32_16x16x32_bf16 v[114:117], v[164:167], v[192:195], v[114:117]
	v_mfma_f32_16x16x32_bf16 v[102:105], v[146:149], v[208:211], v[102:105]
	v_mfma_f32_16x16x32_bf16 v[98:101], v[164:167], v[208:211], v[98:101]
	v_mfma_f32_16x16x32_bf16 v[86:89], v[146:149], v[216:219], v[86:89]
	v_mfma_f32_16x16x32_bf16 v[82:85], v[164:167], v[216:219], v[82:85]
	v_mfma_f32_16x16x32_bf16 v[70:73], v[146:149], v[224:227], v[70:73]
	v_mfma_f32_16x16x32_bf16 v[66:69], v[164:167], v[224:227], v[66:69]
	v_mfma_f32_16x16x32_bf16 v[118:121], v[150:153], v[204:207], v[118:121]
	v_mfma_f32_16x16x32_bf16 v[114:117], v[168:171], v[204:207], v[114:117]
	v_mfma_f32_16x16x32_bf16 v[102:105], v[150:153], v[212:215], v[102:105]
	v_mfma_f32_16x16x32_bf16 v[98:101], v[168:171], v[212:215], v[98:101]
	v_mfma_f32_16x16x32_bf16 v[86:89], v[150:153], v[220:223], v[86:89]
	v_mfma_f32_16x16x32_bf16 v[82:85], v[168:171], v[220:223], v[82:85]
	v_mfma_f32_16x16x32_bf16 v[70:73], v[150:153], v[242:245], v[70:73]
	v_mfma_f32_16x16x32_bf16 v[66:69], v[168:171], v[242:245], v[66:69]
	s_barrier
	s_setprio 0
	s_add_i32 s10, s39, s43
	s_mov_b32 m0, s10
	ds_read_b128 v[192:195], v190 offset:16384
	ds_read_b128 v[204:207], v190 offset:17408
	ds_read_b128 v[208:211], v190 offset:18432
	ds_read_b128 v[212:215], v190 offset:19456
	ds_read_b128 v[216:219], v190 offset:20480
	ds_read_b128 v[220:223], v190 offset:21504
	ds_read_b128 v[224:227], v190 offset:22528
	ds_read_b128 v[242:245], v190 offset:23552
	global_load_lds_dwordx4 v0, s[72:73]
	s_add_i32 m0, s10, 0x2000
	s_add_u32 s10, s72, 0xb0000
	s_addc_u32 s11, s73, 0
	s_add_i32 s30, s30, s43
	global_load_lds_dwordx4 v158, s[72:73]
	s_mov_b32 m0, s30
	s_nop 0
	global_load_lds_dwordx4 v0, s[10:11]
	s_add_i32 m0, s30, 0x2000
	s_nop 0
	global_load_lds_dwordx4 v158, s[10:11]
	s_mov_b32 m0, s46
	s_nop 0
	global_load_lds_dwordx4 v154, s[74:75]
	s_mov_b32 m0, s47
	s_nop 0
	global_load_lds_dwordx4 v156, s[74:75]
	s_waitcnt vmcnt(8) lgkmcnt(0)
	s_setprio 1
	s_barrier
	v_mfma_f32_16x16x32_bf16 v[62:65], v[130:133], v[192:195], v[62:65]
	v_mfma_f32_16x16x32_bf16 v[58:61], v[138:141], v[192:195], v[58:61]
	v_mfma_f32_16x16x32_bf16 v[46:49], v[130:133], v[208:211], v[46:49]
	v_mfma_f32_16x16x32_bf16 v[42:45], v[138:141], v[208:211], v[42:45]
	v_mfma_f32_16x16x32_bf16 v[30:33], v[130:133], v[216:219], v[30:33]
	v_mfma_f32_16x16x32_bf16 v[26:29], v[138:141], v[216:219], v[26:29]
	v_mfma_f32_16x16x32_bf16 v[14:17], v[130:133], v[224:227], v[14:17]
	v_mfma_f32_16x16x32_bf16 v[10:13], v[138:141], v[224:227], v[10:13]
	v_mfma_f32_16x16x32_bf16 v[62:65], v[134:137], v[204:207], v[62:65]
	v_mfma_f32_16x16x32_bf16 v[58:61], v[142:145], v[204:207], v[58:61]
	v_mfma_f32_16x16x32_bf16 v[46:49], v[134:137], v[212:215], v[46:49]
	v_mfma_f32_16x16x32_bf16 v[42:45], v[142:145], v[212:215], v[42:45]
	v_mfma_f32_16x16x32_bf16 v[30:33], v[134:137], v[220:223], v[30:33]
	v_mfma_f32_16x16x32_bf16 v[26:29], v[142:145], v[220:223], v[26:29]
	v_mfma_f32_16x16x32_bf16 v[14:17], v[134:137], v[242:245], v[14:17]
	v_mfma_f32_16x16x32_bf16 v[10:13], v[142:145], v[242:245], v[10:13]
	s_setprio 0
	s_setprio 1
	v_mfma_f32_16x16x32_bf16 v[54:57], v[146:149], v[192:195], v[54:57]
	v_mfma_f32_16x16x32_bf16 v[50:53], v[164:167], v[192:195], v[50:53]
	v_mfma_f32_16x16x32_bf16 v[38:41], v[146:149], v[208:211], v[38:41]
	v_mfma_f32_16x16x32_bf16 v[34:37], v[164:167], v[208:211], v[34:37]
	v_mfma_f32_16x16x32_bf16 v[22:25], v[146:149], v[216:219], v[22:25]
	v_mfma_f32_16x16x32_bf16 v[18:21], v[164:167], v[216:219], v[18:21]
	v_mfma_f32_16x16x32_bf16 v[6:9], v[146:149], v[224:227], v[6:9]
	v_mfma_f32_16x16x32_bf16 v[2:5], v[164:167], v[224:227], v[2:5]
	v_mfma_f32_16x16x32_bf16 v[54:57], v[150:153], v[204:207], v[54:57]
	v_mfma_f32_16x16x32_bf16 v[50:53], v[168:171], v[204:207], v[50:53]
	v_mfma_f32_16x16x32_bf16 v[38:41], v[150:153], v[212:215], v[38:41]
	v_mfma_f32_16x16x32_bf16 v[34:37], v[168:171], v[212:215], v[34:37]
	v_mfma_f32_16x16x32_bf16 v[22:25], v[150:153], v[220:223], v[22:25]
	v_mfma_f32_16x16x32_bf16 v[18:21], v[168:171], v[220:223], v[18:21]
	v_mfma_f32_16x16x32_bf16 v[6:9], v[150:153], v[242:245], v[6:9]
	v_mfma_f32_16x16x32_bf16 v[2:5], v[168:171], v[242:245], v[2:5]
	s_barrier
; #define PG8_STAGE(bufoff, gbase, voff) do { _Pragma("unroll") for (int _i = 0; _i < 2; ++_i) \
;         __builtin_amdgcn_global_load_lds((const gunsigned*)((const gchar*)(gbase) + (voff)[_i]), (LAS unsigned*)(lds + (bufoff) + ldsw + _i * 8192), 16, 0, 0); } while (0)
; #define PG8_LDA(dst, b, h) do { _Pragma("unroll") for (int m = 0; m < 4; ++m) _Pragma("unroll") for (int k = 0; k < 2; ++k) dst[m][k] = *(const LAS bf16x8*)(lds + PG8_SA(b, h) + aoff + m * 2048 + k * 1024); } while (0)
; #define PG8_LDB(dst, b, h) do { _Pragma("unroll") for (int n = 0; n < 2; ++n) _Pragma("unroll") for (int k = 0; k < 2; ++k) dst[n][k] = *(const LAS bf16x8*)(lds + PG8_SB(b, h) + boff + n * 2048 + k * 1024); } while (0)
; #define PG8_MMA(ai, bj, At, Bt) do { __builtin_amdgcn_s_setprio(1); _Pragma("unroll") for (int m = 0; m < 4; ++m) _Pragma("unroll") for (int n = 0; n < 2; ++n) _Pragma("unroll") for (int k = 0; k < 2; ++k) \
;         acc[ai][bj][m][n] = __builtin_amdgcn_mfma_f32_16x16x32_bf16(Bt[n][k], At[m][k], acc[ai][bj][m][n], 0, 0, 0); __builtin_amdgcn_s_setprio(0); } while (0)
; #define PG8_WAIT_V(n) asm volatile("s_waitcnt vmcnt(" #n ")" ::: "memory")
; #define PG8_WAIT_L(n) asm volatile("s_waitcnt lgkmcnt(" #n ")" ::: "memory")
; #define PG8_BAR __builtin_amdgcn_s_barrier()
; #define PG8_SCHED __builtin_amdgcn_sched_barrier(0)
; template <class Epi, class Sched>
; __device__ __forceinline__ void gemm_phase(LAS unsigned char* lds, const int tid, const Gemm g, const Sched& S, const Epi& E) {
;     ...
;             PG8_LDB(B0, 1, 0); PG8_LDB(B1, 1, 1); PG8_SCHED; PG8_LDA(At, 1, 0); PG8_STAGE(PG8_SA(0, 1), a2 + hstep, voffA);
;             PG8_WAIT_V(8); PG8_WAIT_L(0); PG8_BAR; PG8_MMA(0, 0, At, B0); PG8_MMA(0, 1, At, B1); PG8_BAR; PG8_SCHED;
;             PG8_LDA(At, 1, 1); PG8_STAGE(PG8_SB(1, 0), b3, voffB); PG8_STAGE(PG8_SB(1, 1), b3 + hstep, voffB); PG8_STAGE(PG8_SA(1, 0), a3, voffA);
;             PG8_WAIT_V(8); PG8_WAIT_L(0); PG8_BAR; PG8_MMA(1, 0, At, B0); PG8_MMA(1, 1, At, B1); PG8_BAR; PG8_SCHED;
;         }
;         if (wr == 0) PG8_BAR;
	s_setprio 0
	s_add_i32 s30, 0, 0x18000
	s_add_i32 s39, 0, 0x1c000
	v_add_u32_e32 v142, s30, v174
	v_add_u32_e32 v168, s39, v174
	ds_read_b128 v[130:133], v142
	ds_read_b128 v[134:137], v142 offset:1024
	ds_read_b128 v[138:141], v142 offset:2048
	ds_read_b128 v[142:145], v142 offset:3072
	ds_read_b128 v[146:149], v168
	ds_read_b128 v[150:153], v168 offset:1024
	ds_read_b128 v[164:167], v168 offset:2048
	ds_read_b128 v[168:171], v168 offset:3072
	s_add_u32 s10, s74, 0xb0000
	s_addc_u32 s11, s75, 0
	s_mov_b32 m0, s48
	ds_read_b128 v[192:195], v190 offset:32768
	ds_read_b128 v[204:207], v190 offset:33792
	ds_read_b128 v[208:211], v190 offset:34816
	ds_read_b128 v[212:215], v190 offset:35840
	ds_read_b128 v[216:219], v190 offset:36864
	ds_read_b128 v[220:223], v190 offset:37888
	ds_read_b128 v[224:227], v190 offset:38912
	ds_read_b128 v[242:245], v190 offset:39936
	global_load_lds_dwordx4 v154, s[10:11]
	s_mov_b32 m0, s49
	s_nop 0
	global_load_lds_dwordx4 v156, s[10:11]
	s_waitcnt vmcnt(8) lgkmcnt(0)
	s_setprio 1
	s_barrier
	v_mfma_f32_16x16x32_bf16 v[126:129], v[130:133], v[192:195], v[126:129]
	v_mfma_f32_16x16x32_bf16 v[122:125], v[138:141], v[192:195], v[122:125]
	v_mfma_f32_16x16x32_bf16 v[110:113], v[130:133], v[208:211], v[110:113]
	v_mfma_f32_16x16x32_bf16 v[106:109], v[138:141], v[208:211], v[106:109]
	v_mfma_f32_16x16x32_bf16 v[94:97], v[130:133], v[216:219], v[94:97]
	v_mfma_f32_16x16x32_bf16 v[90:93], v[138:141], v[216:219], v[90:93]
	v_mfma_f32_16x16x32_bf16 v[78:81], v[130:133], v[224:227], v[78:81]
	v_mfma_f32_16x16x32_bf16 v[74:77], v[138:141], v[224:227], v[74:77]
	v_mfma_f32_16x16x32_bf16 v[126:129], v[134:137], v[204:207], v[126:129]
	v_mfma_f32_16x16x32_bf16 v[122:125], v[142:145], v[204:207], v[122:125]
	v_mfma_f32_16x16x32_bf16 v[110:113], v[134:137], v[212:215], v[110:113]
	v_mfma_f32_16x16x32_bf16 v[106:109], v[142:145], v[212:215], v[106:109]
	v_mfma_f32_16x16x32_bf16 v[94:97], v[134:137], v[220:223], v[94:97]
	v_mfma_f32_16x16x32_bf16 v[90:93], v[142:145], v[220:223], v[90:93]
	v_mfma_f32_16x16x32_bf16 v[78:81], v[134:137], v[242:245], v[78:81]
	v_mfma_f32_16x16x32_bf16 v[74:77], v[142:145], v[242:245], v[74:77]
	s_setprio 0
	s_setprio 1
	v_mfma_f32_16x16x32_bf16 v[118:121], v[146:149], v[192:195], v[118:121]
	v_mfma_f32_16x16x32_bf16 v[114:117], v[164:167], v[192:195], v[114:117]
	v_mfma_f32_16x16x32_bf16 v[102:105], v[146:149], v[208:211], v[102:105]
	v_mfma_f32_16x16x32_bf16 v[98:101], v[164:167], v[208:211], v[98:101]
	v_mfma_f32_16x16x32_bf16 v[86:89], v[146:149], v[216:219], v[86:89]
	v_mfma_f32_16x16x32_bf16 v[82:85], v[164:167], v[216:219], v[82:85]
	v_mfma_f32_16x16x32_bf16 v[70:73], v[146:149], v[224:227], v[70:73]
	v_mfma_f32_16x16x32_bf16 v[66:69], v[164:167], v[224:227], v[66:69]
	v_mfma_f32_16x16x32_bf16 v[118:121], v[150:153], v[204:207], v[118:121]
	v_mfma_f32_16x16x32_bf16 v[114:117], v[168:171], v[204:207], v[114:117]
	v_mfma_f32_16x16x32_bf16 v[102:105], v[150:153], v[212:215], v[102:105]
	v_mfma_f32_16x16x32_bf16 v[98:101], v[168:171], v[212:215], v[98:101]
	v_mfma_f32_16x16x32_bf16 v[86:89], v[150:153], v[220:223], v[86:89]
	v_mfma_f32_16x16x32_bf16 v[82:85], v[168:171], v[220:223], v[82:85]
	v_mfma_f32_16x16x32_bf16 v[70:73], v[150:153], v[242:245], v[70:73]
	v_mfma_f32_16x16x32_bf16 v[66:69], v[168:171], v[242:245], v[66:69]
	s_barrier
	s_setprio 0
	s_add_i32 s10, s30, s43
	s_mov_b32 m0, s10
	ds_read_b128 v[192:195], v190 offset:49152
	ds_read_b128 v[204:207], v190 offset:50176
	ds_read_b128 v[208:211], v190 offset:51200
	ds_read_b128 v[212:215], v190 offset:52224
	ds_read_b128 v[216:219], v190 offset:53248
	ds_read_b128 v[220:223], v190 offset:54272
	ds_read_b128 v[224:227], v190 offset:55296
	ds_read_b128 v[242:245], v190 offset:56320
	global_load_lds_dwordx4 v201, s[72:73]
	s_add_i32 m0, s10, 0x2000
	s_add_u32 s10, s72, 0xb0080
	s_addc_u32 s11, s73, 0
	s_add_i32 s30, s39, s43
	global_load_lds_dwordx4 v247, s[72:73]
	s_mov_b32 m0, s30
	s_nop 0
	global_load_lds_dwordx4 v0, s[10:11]
	s_add_i32 m0, s30, 0x2000
	s_nop 0
	global_load_lds_dwordx4 v158, s[10:11]
	s_mov_b32 m0, s53
	s_nop 0
	global_load_lds_dwordx4 v249, s[74:75]
	s_mov_b32 m0, s54
	s_nop 0
	global_load_lds_dwordx4 v251, s[74:75]
	s_waitcnt vmcnt(8) lgkmcnt(0)
	s_setprio 1
	s_barrier
	v_mfma_f32_16x16x32_bf16 v[62:65], v[130:133], v[192:195], v[62:65]
	v_mfma_f32_16x16x32_bf16 v[58:61], v[138:141], v[192:195], v[58:61]
	v_mfma_f32_16x16x32_bf16 v[46:49], v[130:133], v[208:211], v[46:49]
	v_mfma_f32_16x16x32_bf16 v[42:45], v[138:141], v[208:211], v[42:45]
	v_mfma_f32_16x16x32_bf16 v[30:33], v[130:133], v[216:219], v[30:33]
	v_mfma_f32_16x16x32_bf16 v[26:29], v[138:141], v[216:219], v[26:29]
	v_mfma_f32_16x16x32_bf16 v[14:17], v[130:133], v[224:227], v[14:17]
	v_mfma_f32_16x16x32_bf16 v[10:13], v[138:141], v[224:227], v[10:13]
	v_mfma_f32_16x16x32_bf16 v[62:65], v[134:137], v[204:207], v[62:65]
	v_mfma_f32_16x16x32_bf16 v[58:61], v[142:145], v[204:207], v[58:61]
	v_mfma_f32_16x16x32_bf16 v[46:49], v[134:137], v[212:215], v[46:49]
	v_mfma_f32_16x16x32_bf16 v[42:45], v[142:145], v[212:215], v[42:45]
	v_mfma_f32_16x16x32_bf16 v[30:33], v[134:137], v[220:223], v[30:33]
	v_mfma_f32_16x16x32_bf16 v[26:29], v[142:145], v[220:223], v[26:29]
	v_mfma_f32_16x16x32_bf16 v[14:17], v[134:137], v[242:245], v[14:17]
	v_mfma_f32_16x16x32_bf16 v[10:13], v[142:145], v[242:245], v[10:13]
	s_setprio 0
	s_setprio 1
	v_mfma_f32_16x16x32_bf16 v[54:57], v[146:149], v[192:195], v[54:57]
	v_mfma_f32_16x16x32_bf16 v[50:53], v[164:167], v[192:195], v[50:53]
	v_mfma_f32_16x16x32_bf16 v[38:41], v[146:149], v[208:211], v[38:41]
	v_mfma_f32_16x16x32_bf16 v[34:37], v[164:167], v[208:211], v[34:37]
	v_mfma_f32_16x16x32_bf16 v[22:25], v[146:149], v[216:219], v[22:25]
	v_mfma_f32_16x16x32_bf16 v[18:21], v[164:167], v[216:219], v[18:21]
	v_mfma_f32_16x16x32_bf16 v[6:9], v[146:149], v[224:227], v[6:9]
	v_mfma_f32_16x16x32_bf16 v[2:5], v[164:167], v[224:227], v[2:5]
	v_mfma_f32_16x16x32_bf16 v[54:57], v[150:153], v[204:207], v[54:57]
	v_mfma_f32_16x16x32_bf16 v[50:53], v[168:171], v[204:207], v[50:53]
	v_mfma_f32_16x16x32_bf16 v[38:41], v[150:153], v[212:215], v[38:41]
	v_mfma_f32_16x16x32_bf16 v[34:37], v[168:171], v[212:215], v[34:37]
	v_mfma_f32_16x16x32_bf16 v[22:25], v[150:153], v[220:223], v[22:25]
	v_mfma_f32_16x16x32_bf16 v[18:21], v[168:171], v[220:223], v[18:21]
	v_mfma_f32_16x16x32_bf16 v[6:9], v[150:153], v[242:245], v[6:9]
	v_mfma_f32_16x16x32_bf16 v[2:5], v[168:171], v[242:245], v[2:5]
	s_barrier
	s_setprio 0
	s_add_i32 s29, s29, 2
	s_add_u32 s31, s31, 0x100
	s_addc_u32 s93, s93, 0
	s_cmp_gt_u32 s29, 41
	s_mov_b64 s[10:11], vcc
	s_cbranch_scc0 .LBB0_319
	s_and_b64 vcc, exec, s[16:17]
	s_cbranch_vccz .LBB0_322
	s_barrier

; #define PG8_STAGE(bufoff, gbase, voff) do { _Pragma("unroll") for (int _i = 0; _i < 2; ++_i) \
;         __builtin_amdgcn_global_load_lds((const gunsigned*)((const gchar*)(gbase) + (voff)[_i]), (LAS unsigned*)(lds + (bufoff) + ldsw + _i * 8192), 16, 0, 0); } while (0)
; #define PG8_LDA(dst, b, h) do { _Pragma("unroll") for (int m = 0; m < 4; ++m) _Pragma("unroll") for (int k = 0; k < 2; ++k) dst[m][k] = *(const LAS bf16x8*)(lds + PG8_SA(b, h) + aoff + m * 2048 + k * 1024); } while (0)
; #define PG8_LDB(dst, b, h) do { _Pragma("unroll") for (int n = 0; n < 2; ++n) _Pragma("unroll") for (int k = 0; k < 2; ++k) dst[n][k] = *(const LAS bf16x8*)(lds + PG8_SB(b, h) + boff + n * 2048 + k * 1024); } while (0)
; #define PG8_MMA(ai, bj, At, Bt) do { __builtin_amdgcn_s_setprio(1); _Pragma("unroll") for (int m = 0; m < 4; ++m) _Pragma("unroll") for (int n = 0; n < 2; ++n) _Pragma("unroll") for (int k = 0; k < 2; ++k) \
;         acc[ai][bj][m][n] = __builtin_amdgcn_mfma_f32_16x16x32_bf16(Bt[n][k], At[m][k], acc[ai][bj][m][n], 0, 0, 0); __builtin_amdgcn_s_setprio(0); } while (0)
; #define PG8_WAIT_V(n) asm volatile("s_waitcnt vmcnt(" #n ")" ::: "memory")
; #define PG8_WAIT_L(n) asm volatile("s_waitcnt lgkmcnt(" #n ")" ::: "memory")
; #define PG8_BAR __builtin_amdgcn_s_barrier()
; #define PG8_SCHED __builtin_amdgcn_sched_barrier(0)
; template <class Epi, class Sched>
; __device__ __forceinline__ void gemm_phase(LAS unsigned char* lds, const int tid, const Gemm g, const Sched& S, const Epi& E) {
;     ...
;             const gchar* a1 = cA + (size_t)(t + 1) * kstep;
;             const gchar* a2 = last ? nA : cA + (size_t)(t + 2) * kstep; const gchar* b2 = last ? nB : cB + (size_t)(t + 2) * kstep;
;             const gchar* a3 = a2 + kstep; const gchar* b3 = b2 + kstep;
;             PG8_LDB(B0, 0, 0); PG8_LDB(B1, 0, 1); PG8_SCHED; PG8_LDA(At, 0, 0); PG8_STAGE(PG8_SA(1, 1), a1 + hstep, voffA);
;             PG8_WAIT_V(8); PG8_WAIT_L(0); PG8_BAR; PG8_MMA(0, 0, At, B0); PG8_MMA(0, 1, At, B1); PG8_BAR; PG8_SCHED;
;             PG8_LDA(At, 0, 1); PG8_STAGE(PG8_SB(0, 0), b2, voffB); PG8_STAGE(PG8_SB(0, 1), b2 + hstep, voffB); PG8_STAGE(PG8_SA(0, 0), a2, voffA);
;             PG8_WAIT_V(8); PG8_WAIT_L(0); PG8_BAR; PG8_MMA(1, 0, At, B0); PG8_MMA(1, 1, At, B1); PG8_BAR; PG8_SCHED;
.LBB0_369:
	s_add_u32 s20, s16, 0xfffc0080
	s_addc_u32 s21, s17, -1
	s_add_i32 s29, 0, 0x10000
	s_cmp_eq_u32 s31, 12
	s_cselect_b32 s57, s11, s21
	s_cselect_b32 s56, s12, s20
	v_add_u32_e32 v140, s29, v145
	s_cselect_b32 s21, s9, s24
	s_cselect_b32 s20, s15, s23
	s_add_i32 s30, 0, 0x14000
	ds_read_b128 v[146:149], v140
	ds_read_b128 v[156:159], v140 offset:1024
	ds_read_b128 v[160:163], v140 offset:2048
	ds_read_b128 v[164:167], v140 offset:3072
	v_add_u32_e32 v140, s30, v145
	ds_read_b128 v[168:171], v140
	ds_read_b128 v[172:175], v140 offset:1024
	ds_read_b128 v[176:179], v140 offset:2048
	ds_read_b128 v[180:183], v140 offset:3072
	s_add_i32 m0, s73, 0xc000
	ds_read_b128 v[184:187], v155
	ds_read_b128 v[188:191], v155 offset:1024
	ds_read_b128 v[192:195], v155 offset:2048
	ds_read_b128 v[204:207], v155 offset:3072
	ds_read_b128 v[208:211], v155 offset:4096
	ds_read_b128 v[212:215], v155 offset:5120
	ds_read_b128 v[216:219], v155 offset:6144
	ds_read_b128 v[220:223], v155 offset:7168
	global_load_lds_dwordx4 v138, s[16:17]
	s_add_i32 m0, s73, 0xe000
	s_nop 0
	global_load_lds_dwordx4 v136, s[16:17]
	s_waitcnt vmcnt(8) lgkmcnt(0)
	s_setprio 1
	s_barrier
	v_mfma_f32_16x16x32_bf16 v[126:129], v[146:149], v[184:187], v[126:129]
	v_mfma_f32_16x16x32_bf16 v[118:121], v[160:163], v[184:187], v[118:121]
	v_mfma_f32_16x16x32_bf16 v[110:113], v[146:149], v[192:195], v[110:113]
	v_mfma_f32_16x16x32_bf16 v[102:105], v[160:163], v[192:195], v[102:105]
	v_mfma_f32_16x16x32_bf16 v[94:97], v[146:149], v[208:211], v[94:97]
	v_mfma_f32_16x16x32_bf16 v[86:89], v[160:163], v[208:211], v[86:89]
	v_mfma_f32_16x16x32_bf16 v[78:81], v[146:149], v[216:219], v[78:81]
	v_mfma_f32_16x16x32_bf16 v[70:73], v[160:163], v[216:219], v[70:73]
	v_mfma_f32_16x16x32_bf16 v[126:129], v[156:159], v[188:191], v[126:129]
	v_mfma_f32_16x16x32_bf16 v[118:121], v[164:167], v[188:191], v[118:121]
	v_mfma_f32_16x16x32_bf16 v[110:113], v[156:159], v[204:207], v[110:113]
	v_mfma_f32_16x16x32_bf16 v[102:105], v[164:167], v[204:207], v[102:105]
	v_mfma_f32_16x16x32_bf16 v[94:97], v[156:159], v[212:215], v[94:97]
	v_mfma_f32_16x16x32_bf16 v[86:89], v[164:167], v[212:215], v[86:89]
	v_mfma_f32_16x16x32_bf16 v[78:81], v[156:159], v[220:223], v[78:81]
	v_mfma_f32_16x16x32_bf16 v[70:73], v[164:167], v[220:223], v[70:73]
	s_setprio 0
	s_setprio 1
	v_mfma_f32_16x16x32_bf16 v[122:125], v[168:171], v[184:187], v[122:125]
	v_mfma_f32_16x16x32_bf16 v[114:117], v[176:179], v[184:187], v[114:117]
	v_mfma_f32_16x16x32_bf16 v[106:109], v[168:171], v[192:195], v[106:109]
	v_mfma_f32_16x16x32_bf16 v[98:101], v[176:179], v[192:195], v[98:101]
	v_mfma_f32_16x16x32_bf16 v[90:93], v[168:171], v[208:211], v[90:93]
	v_mfma_f32_16x16x32_bf16 v[82:85], v[176:179], v[208:211], v[82:85]
	v_mfma_f32_16x16x32_bf16 v[74:77], v[168:171], v[216:219], v[74:77]
	v_mfma_f32_16x16x32_bf16 v[66:69], v[176:179], v[216:219], v[66:69]
	v_mfma_f32_16x16x32_bf16 v[122:125], v[172:175], v[188:191], v[122:125]
	v_mfma_f32_16x16x32_bf16 v[114:117], v[180:183], v[188:191], v[114:117]
	v_mfma_f32_16x16x32_bf16 v[106:109], v[172:175], v[204:207], v[106:109]
	v_mfma_f32_16x16x32_bf16 v[98:101], v[180:183], v[204:207], v[98:101]
	v_mfma_f32_16x16x32_bf16 v[90:93], v[172:175], v[212:215], v[90:93]
	v_mfma_f32_16x16x32_bf16 v[82:85], v[180:183], v[212:215], v[82:85]
	v_mfma_f32_16x16x32_bf16 v[74:77], v[172:175], v[220:223], v[74:77]
	v_mfma_f32_16x16x32_bf16 v[66:69], v[180:183], v[220:223], v[66:69]
	s_barrier
	s_setprio 0
	s_add_i32 s29, s29, s43
	s_mov_b32 m0, s29
	ds_read_b128 v[184:187], v155 offset:16384
	ds_read_b128 v[188:191], v155 offset:17408
	ds_read_b128 v[192:195], v155 offset:18432
	ds_read_b128 v[204:207], v155 offset:19456
	ds_read_b128 v[208:211], v155 offset:20480
	ds_read_b128 v[212:215], v155 offset:21504
	ds_read_b128 v[216:219], v155 offset:22528
	ds_read_b128 v[220:223], v155 offset:23552
	global_load_lds_dwordx4 v0, s[20:21]
	s_add_i32 m0, s29, 0x2000
	s_add_u32 s46, s20, 0x40000
	s_addc_u32 s47, s21, 0
	s_add_i32 s29, s30, s43
	global_load_lds_dwordx4 v130, s[20:21]
	s_mov_b32 m0, s29
	s_nop 0
	global_load_lds_dwordx4 v0, s[46:47]
	s_add_i32 m0, s29, 0x2000
	s_nop 0
	global_load_lds_dwordx4 v130, s[46:47]
	s_mov_b32 m0, s73
	s_nop 0
	global_load_lds_dwordx4 v134, s[56:57]
	s_mov_b32 m0, s74
	s_nop 0
	global_load_lds_dwordx4 v132, s[56:57]
	s_waitcnt vmcnt(8) lgkmcnt(0)
	s_setprio 1
	s_barrier
	v_mfma_f32_16x16x32_bf16 v[62:65], v[146:149], v[184:187], v[62:65]
	v_mfma_f32_16x16x32_bf16 v[54:57], v[160:163], v[184:187], v[54:57]
	v_mfma_f32_16x16x32_bf16 v[46:49], v[146:149], v[192:195], v[46:49]
	v_mfma_f32_16x16x32_bf16 v[38:41], v[160:163], v[192:195], v[38:41]
	v_mfma_f32_16x16x32_bf16 v[30:33], v[146:149], v[208:211], v[30:33]
	v_mfma_f32_16x16x32_bf16 v[22:25], v[160:163], v[208:211], v[22:25]
	v_mfma_f32_16x16x32_bf16 v[14:17], v[146:149], v[216:219], v[14:17]
	v_mfma_f32_16x16x32_bf16 v[6:9], v[160:163], v[216:219], v[6:9]
	v_mfma_f32_16x16x32_bf16 v[62:65], v[156:159], v[188:191], v[62:65]
	v_mfma_f32_16x16x32_bf16 v[54:57], v[164:167], v[188:191], v[54:57]
	v_mfma_f32_16x16x32_bf16 v[46:49], v[156:159], v[204:207], v[46:49]
	v_mfma_f32_16x16x32_bf16 v[38:41], v[164:167], v[204:207], v[38:41]
	v_mfma_f32_16x16x32_bf16 v[30:33], v[156:159], v[212:215], v[30:33]
	v_mfma_f32_16x16x32_bf16 v[22:25], v[164:167], v[212:215], v[22:25]
	v_mfma_f32_16x16x32_bf16 v[14:17], v[156:159], v[220:223], v[14:17]
	v_mfma_f32_16x16x32_bf16 v[6:9], v[164:167], v[220:223], v[6:9]
	s_setprio 0
	s_setprio 1
	v_mfma_f32_16x16x32_bf16 v[58:61], v[168:171], v[184:187], v[58:61]
	v_mfma_f32_16x16x32_bf16 v[50:53], v[176:179], v[184:187], v[50:53]
	v_mfma_f32_16x16x32_bf16 v[42:45], v[168:171], v[192:195], v[42:45]
	v_mfma_f32_16x16x32_bf16 v[34:37], v[176:179], v[192:195], v[34:37]
	v_mfma_f32_16x16x32_bf16 v[26:29], v[168:171], v[208:211], v[26:29]
	v_mfma_f32_16x16x32_bf16 v[18:21], v[176:179], v[208:211], v[18:21]
	v_mfma_f32_16x16x32_bf16 v[10:13], v[168:171], v[216:219], v[10:13]
	v_mfma_f32_16x16x32_bf16 v[2:5], v[176:179], v[216:219], v[2:5]
	v_mfma_f32_16x16x32_bf16 v[58:61], v[172:175], v[188:191], v[58:61]
	v_mfma_f32_16x16x32_bf16 v[50:53], v[180:183], v[188:191], v[50:53]
	v_mfma_f32_16x16x32_bf16 v[42:45], v[172:175], v[204:207], v[42:45]
	v_mfma_f32_16x16x32_bf16 v[34:37], v[180:183], v[204:207], v[34:37]
	v_mfma_f32_16x16x32_bf16 v[26:29], v[172:175], v[212:215], v[26:29]
	v_mfma_f32_16x16x32_bf16 v[18:21], v[180:183], v[212:215], v[18:21]
	v_mfma_f32_16x16x32_bf16 v[10:13], v[172:175], v[220:223], v[10:13]
	v_mfma_f32_16x16x32_bf16 v[2:5], v[180:183], v[220:223], v[2:5]
	s_barrier
; #define PG8_STAGE(bufoff, gbase, voff) do { _Pragma("unroll") for (int _i = 0; _i < 2; ++_i) \
;         __builtin_amdgcn_global_load_lds((const gunsigned*)((const gchar*)(gbase) + (voff)[_i]), (LAS unsigned*)(lds + (bufoff) + ldsw + _i * 8192), 16, 0, 0); } while (0)
; #define PG8_LDA(dst, b, h) do { _Pragma("unroll") for (int m = 0; m < 4; ++m) _Pragma("unroll") for (int k = 0; k < 2; ++k) dst[m][k] = *(const LAS bf16x8*)(lds + PG8_SA(b, h) + aoff + m * 2048 + k * 1024); } while (0)
; #define PG8_LDB(dst, b, h) do { _Pragma("unroll") for (int n = 0; n < 2; ++n) _Pragma("unroll") for (int k = 0; k < 2; ++k) dst[n][k] = *(const LAS bf16x8*)(lds + PG8_SB(b, h) + boff + n * 2048 + k * 1024); } while (0)
; #define PG8_MMA(ai, bj, At, Bt) do { __builtin_amdgcn_s_setprio(1); _Pragma("unroll") for (int m = 0; m < 4; ++m) _Pragma("unroll") for (int n = 0; n < 2; ++n) _Pragma("unroll") for (int k = 0; k < 2; ++k) \
;         acc[ai][bj][m][n] = __builtin_amdgcn_mfma_f32_16x16x32_bf16(Bt[n][k], At[m][k], acc[ai][bj][m][n], 0, 0, 0); __builtin_amdgcn_s_setprio(0); } while (0)
; #define PG8_WAIT_V(n) asm volatile("s_waitcnt vmcnt(" #n ")" ::: "memory")
; #define PG8_WAIT_L(n) asm volatile("s_waitcnt lgkmcnt(" #n ")" ::: "memory")
; #define PG8_BAR __builtin_amdgcn_s_barrier()
; #define PG8_SCHED __builtin_amdgcn_sched_barrier(0)
; template <class Epi, class Sched>
; __device__ __forceinline__ void gemm_phase(LAS unsigned char* lds, const int tid, const Gemm g, const Sched& S, const Epi& E) {
;     ...
;             PG8_LDB(B0, 1, 0); PG8_LDB(B1, 1, 1); PG8_SCHED; PG8_LDA(At, 1, 0); PG8_STAGE(PG8_SA(0, 1), a2 + hstep, voffA);
;             PG8_WAIT_V(8); PG8_WAIT_L(0); PG8_BAR; PG8_MMA(0, 0, At, B0); PG8_MMA(0, 1, At, B1); PG8_BAR; PG8_SCHED;
;             PG8_LDA(At, 1, 1); PG8_STAGE(PG8_SB(1, 0), b3, voffB); PG8_STAGE(PG8_SB(1, 1), b3 + hstep, voffB); PG8_STAGE(PG8_SA(1, 0), a3, voffA);
;             PG8_WAIT_V(8); PG8_WAIT_L(0); PG8_BAR; PG8_MMA(1, 0, At, B0); PG8_MMA(1, 1, At, B1); PG8_BAR; PG8_SCHED;
;         }
;         if (wr == 0) PG8_BAR;
	s_setprio 0
	s_add_i32 s29, 0, 0x18000
	v_add_u32_e32 v142, s29, v145
	s_add_i32 s30, 0, 0x1c000
	ds_read_b128 v[146:149], v142
	ds_read_b128 v[156:159], v142 offset:1024
	ds_read_b128 v[160:163], v142 offset:2048
	ds_read_b128 v[164:167], v142 offset:3072
	v_add_u32_e32 v142, s30, v145
	ds_read_b128 v[168:171], v142
	ds_read_b128 v[172:175], v142 offset:1024
	ds_read_b128 v[176:179], v142 offset:2048
	ds_read_b128 v[180:183], v142 offset:3072
	s_add_u32 s46, s56, 0x40000
	s_addc_u32 s47, s57, 0
	s_mov_b32 m0, s75
	ds_read_b128 v[184:187], v155 offset:32768
	ds_read_b128 v[188:191], v155 offset:33792
	ds_read_b128 v[192:195], v155 offset:34816
	ds_read_b128 v[204:207], v155 offset:35840
	ds_read_b128 v[208:211], v155 offset:36864
	ds_read_b128 v[212:215], v155 offset:37888
	ds_read_b128 v[216:219], v155 offset:38912
	ds_read_b128 v[220:223], v155 offset:39936
	global_load_lds_dwordx4 v134, s[46:47]
	s_mov_b32 m0, s92
	s_nop 0
	global_load_lds_dwordx4 v132, s[46:47]
	s_waitcnt vmcnt(8) lgkmcnt(0)
	s_setprio 1
	s_barrier
	v_mfma_f32_16x16x32_bf16 v[126:129], v[146:149], v[184:187], v[126:129]
	v_mfma_f32_16x16x32_bf16 v[118:121], v[160:163], v[184:187], v[118:121]
	v_mfma_f32_16x16x32_bf16 v[110:113], v[146:149], v[192:195], v[110:113]
	v_mfma_f32_16x16x32_bf16 v[102:105], v[160:163], v[192:195], v[102:105]
	v_mfma_f32_16x16x32_bf16 v[94:97], v[146:149], v[208:211], v[94:97]
	v_mfma_f32_16x16x32_bf16 v[86:89], v[160:163], v[208:211], v[86:89]
	v_mfma_f32_16x16x32_bf16 v[78:81], v[146:149], v[216:219], v[78:81]
	v_mfma_f32_16x16x32_bf16 v[70:73], v[160:163], v[216:219], v[70:73]
	v_mfma_f32_16x16x32_bf16 v[126:129], v[156:159], v[188:191], v[126:129]
	v_mfma_f32_16x16x32_bf16 v[118:121], v[164:167], v[188:191], v[118:121]
	v_mfma_f32_16x16x32_bf16 v[110:113], v[156:159], v[204:207], v[110:113]
	v_mfma_f32_16x16x32_bf16 v[102:105], v[164:167], v[204:207], v[102:105]
	v_mfma_f32_16x16x32_bf16 v[94:97], v[156:159], v[212:215], v[94:97]
	v_mfma_f32_16x16x32_bf16 v[86:89], v[164:167], v[212:215], v[86:89]
	v_mfma_f32_16x16x32_bf16 v[78:81], v[156:159], v[220:223], v[78:81]
	v_mfma_f32_16x16x32_bf16 v[70:73], v[164:167], v[220:223], v[70:73]
	s_setprio 0
	s_setprio 1
	v_mfma_f32_16x16x32_bf16 v[122:125], v[168:171], v[184:187], v[122:125]
	v_mfma_f32_16x16x32_bf16 v[114:117], v[176:179], v[184:187], v[114:117]
	v_mfma_f32_16x16x32_bf16 v[106:109], v[168:171], v[192:195], v[106:109]
	v_mfma_f32_16x16x32_bf16 v[98:101], v[176:179], v[192:195], v[98:101]
	v_mfma_f32_16x16x32_bf16 v[90:93], v[168:171], v[208:211], v[90:93]
	v_mfma_f32_16x16x32_bf16 v[82:85], v[176:179], v[208:211], v[82:85]
	v_mfma_f32_16x16x32_bf16 v[74:77], v[168:171], v[216:219], v[74:77]
	v_mfma_f32_16x16x32_bf16 v[66:69], v[176:179], v[216:219], v[66:69]
	v_mfma_f32_16x16x32_bf16 v[122:125], v[172:175], v[188:191], v[122:125]
	v_mfma_f32_16x16x32_bf16 v[114:117], v[180:183], v[188:191], v[114:117]
	v_mfma_f32_16x16x32_bf16 v[106:109], v[172:175], v[204:207], v[106:109]
	v_mfma_f32_16x16x32_bf16 v[98:101], v[180:183], v[204:207], v[98:101]
	v_mfma_f32_16x16x32_bf16 v[90:93], v[172:175], v[212:215], v[90:93]
	v_mfma_f32_16x16x32_bf16 v[82:85], v[180:183], v[212:215], v[82:85]
	v_mfma_f32_16x16x32_bf16 v[74:77], v[172:175], v[220:223], v[74:77]
	v_mfma_f32_16x16x32_bf16 v[66:69], v[180:183], v[220:223], v[66:69]
	s_barrier
	s_setprio 0
	s_add_i32 s29, s29, s43
	s_mov_b32 m0, s29
	ds_read_b128 v[184:187], v155 offset:49152
	ds_read_b128 v[188:191], v155 offset:50176
	ds_read_b128 v[192:195], v155 offset:51200
	ds_read_b128 v[204:207], v155 offset:52224
	ds_read_b128 v[208:211], v155 offset:53248
	ds_read_b128 v[212:215], v155 offset:54272
	ds_read_b128 v[216:219], v155 offset:55296
	ds_read_b128 v[220:223], v155 offset:56320
	global_load_lds_dwordx4 v141, s[20:21]
	s_add_i32 m0, s29, 0x2000
	s_add_i32 s29, s30, s43
	global_load_lds_dwordx4 v153, s[20:21]
	s_add_u32 s20, s20, 0x40080
	s_addc_u32 s21, s21, 0
	s_mov_b32 m0, s29
	s_nop 0
	global_load_lds_dwordx4 v0, s[20:21]
	s_add_i32 m0, s29, 0x2000
	s_nop 0
	global_load_lds_dwordx4 v130, s[20:21]
	s_mov_b32 m0, s93
	s_nop 0
	global_load_lds_dwordx4 v201, s[56:57]
	s_mov_b32 m0, s44
	s_nop 0
	global_load_lds_dwordx4 v225, s[56:57]
	s_waitcnt vmcnt(8) lgkmcnt(0)
	s_setprio 1
	s_barrier
	v_mfma_f32_16x16x32_bf16 v[62:65], v[146:149], v[184:187], v[62:65]
	v_mfma_f32_16x16x32_bf16 v[54:57], v[160:163], v[184:187], v[54:57]
	v_mfma_f32_16x16x32_bf16 v[46:49], v[146:149], v[192:195], v[46:49]
	v_mfma_f32_16x16x32_bf16 v[38:41], v[160:163], v[192:195], v[38:41]
	v_mfma_f32_16x16x32_bf16 v[30:33], v[146:149], v[208:211], v[30:33]
	v_mfma_f32_16x16x32_bf16 v[22:25], v[160:163], v[208:211], v[22:25]
	v_mfma_f32_16x16x32_bf16 v[14:17], v[146:149], v[216:219], v[14:17]
	v_mfma_f32_16x16x32_bf16 v[6:9], v[160:163], v[216:219], v[6:9]
	v_mfma_f32_16x16x32_bf16 v[62:65], v[156:159], v[188:191], v[62:65]
	v_mfma_f32_16x16x32_bf16 v[54:57], v[164:167], v[188:191], v[54:57]
	v_mfma_f32_16x16x32_bf16 v[46:49], v[156:159], v[204:207], v[46:49]
	v_mfma_f32_16x16x32_bf16 v[38:41], v[164:167], v[204:207], v[38:41]
	v_mfma_f32_16x16x32_bf16 v[30:33], v[156:159], v[212:215], v[30:33]
	v_mfma_f32_16x16x32_bf16 v[22:25], v[164:167], v[212:215], v[22:25]
	v_mfma_f32_16x16x32_bf16 v[14:17], v[156:159], v[220:223], v[14:17]
	v_mfma_f32_16x16x32_bf16 v[6:9], v[164:167], v[220:223], v[6:9]
	s_setprio 0
	s_setprio 1
	v_mfma_f32_16x16x32_bf16 v[58:61], v[168:171], v[184:187], v[58:61]
	v_mfma_f32_16x16x32_bf16 v[50:53], v[176:179], v[184:187], v[50:53]
	v_mfma_f32_16x16x32_bf16 v[42:45], v[168:171], v[192:195], v[42:45]
	v_mfma_f32_16x16x32_bf16 v[34:37], v[176:179], v[192:195], v[34:37]
	v_mfma_f32_16x16x32_bf16 v[26:29], v[168:171], v[208:211], v[26:29]
	v_mfma_f32_16x16x32_bf16 v[18:21], v[176:179], v[208:211], v[18:21]
	v_mfma_f32_16x16x32_bf16 v[10:13], v[168:171], v[216:219], v[10:13]
	v_mfma_f32_16x16x32_bf16 v[2:5], v[176:179], v[216:219], v[2:5]
	v_mfma_f32_16x16x32_bf16 v[58:61], v[172:175], v[188:191], v[58:61]
	v_mfma_f32_16x16x32_bf16 v[50:53], v[180:183], v[188:191], v[50:53]
	v_mfma_f32_16x16x32_bf16 v[42:45], v[172:175], v[204:207], v[42:45]
	v_mfma_f32_16x16x32_bf16 v[34:37], v[180:183], v[204:207], v[34:37]
	v_mfma_f32_16x16x32_bf16 v[26:29], v[172:175], v[212:215], v[26:29]
	v_mfma_f32_16x16x32_bf16 v[18:21], v[180:183], v[212:215], v[18:21]
	v_mfma_f32_16x16x32_bf16 v[10:13], v[172:175], v[220:223], v[10:13]
	v_mfma_f32_16x16x32_bf16 v[2:5], v[180:183], v[220:223], v[2:5]
	s_barrier
	s_setprio 0
	s_add_i32 s31, s31, 2
	s_add_u32 s23, s23, 0x100
	s_addc_u32 s24, s24, 0
	s_add_u32 s16, s16, 0x100
	s_addc_u32 s17, s17, 0
	s_cmp_gt_u32 s31, 13
	s_cbranch_scc0 .LBB0_369
	s_and_b64 vcc, exec, s[6:7]
	s_cbranch_vccz .LBB0_372
	s_barrier

; #define PG8_STAGE(bufoff, gbase, voff) do { _Pragma("unroll") for (int _i = 0; _i < 2; ++_i) \
;         __builtin_amdgcn_global_load_lds((const gunsigned*)((const gchar*)(gbase) + (voff)[_i]), (LAS unsigned*)(lds + (bufoff) + ldsw + _i * 8192), 16, 0, 0); } while (0)
; #define PG8_LDA(dst, b, h) do { _Pragma("unroll") for (int m = 0; m < 4; ++m) _Pragma("unroll") for (int k = 0; k < 2; ++k) dst[m][k] = *(const LAS bf16x8*)(lds + PG8_SA(b, h) + aoff + m * 2048 + k * 1024); } while (0)
; #define PG8_LDB(dst, b, h) do { _Pragma("unroll") for (int n = 0; n < 2; ++n) _Pragma("unroll") for (int k = 0; k < 2; ++k) dst[n][k] = *(const LAS bf16x8*)(lds + PG8_SB(b, h) + boff + n * 2048 + k * 1024); } while (0)
; #define PG8_MMA(ai, bj, At, Bt) do { __builtin_amdgcn_s_setprio(1); _Pragma("unroll") for (int m = 0; m < 4; ++m) _Pragma("unroll") for (int n = 0; n < 2; ++n) _Pragma("unroll") for (int k = 0; k < 2; ++k) \
;         acc[ai][bj][m][n] = __builtin_amdgcn_mfma_f32_16x16x32_bf16(Bt[n][k], At[m][k], acc[ai][bj][m][n], 0, 0, 0); __builtin_amdgcn_s_setprio(0); } while (0)
; #define PG8_WAIT_V(n) asm volatile("s_waitcnt vmcnt(" #n ")" ::: "memory")
; #define PG8_WAIT_L(n) asm volatile("s_waitcnt lgkmcnt(" #n ")" ::: "memory")
; #define PG8_BAR __builtin_amdgcn_s_barrier()
; #define PG8_SCHED __builtin_amdgcn_sched_barrier(0)
; template <class Epi, class Sched>
; __device__ __forceinline__ void gemm_phase(LAS unsigned char* lds, const int tid, const Gemm g, const Sched& S, const Epi& E) {
;     ...
;         for (int t = 0; t < nt; t += 2) {
;             const bool last = (t == nt - 2);
;             const gchar* a1 = cA + (size_t)(t + 1) * kstep;
;             const gchar* a2 = last ? nA : cA + (size_t)(t + 2) * kstep; const gchar* b2 = last ? nB : cB + (size_t)(t + 2) * kstep;
;             const gchar* a3 = a2 + kstep; const gchar* b3 = b2 + kstep;
;             PG8_LDB(B0, 0, 0); PG8_LDB(B1, 0, 1); PG8_SCHED; PG8_LDA(At, 0, 0); PG8_STAGE(PG8_SA(1, 1), a1 + hstep, voffA);
;             PG8_WAIT_V(8); PG8_WAIT_L(0); PG8_BAR; PG8_MMA(0, 0, At, B0); PG8_MMA(0, 1, At, B1); PG8_BAR; PG8_SCHED;
;             PG8_LDA(At, 0, 1); PG8_STAGE(PG8_SB(0, 0), b2, voffB); PG8_STAGE(PG8_SB(0, 1), b2 + hstep, voffB); PG8_STAGE(PG8_SA(0, 0), a2, voffA);
;             PG8_WAIT_V(8); PG8_WAIT_L(0); PG8_BAR; PG8_MMA(1, 0, At, B0); PG8_MMA(1, 1, At, B1); PG8_BAR; PG8_SCHED;
.LBB0_397:
	s_add_u32 s20, s92, 0xfffc0080
	s_addc_u32 s21, s93, -1
	s_add_i32 s29, 0, 0x10000
	s_cmp_eq_u32 s53, 12
	s_cselect_b32 s73, s1, s21
	s_cselect_b32 s72, s31, s20
	s_cselect_b32 s21, s17, s52
	s_cselect_b32 s20, s50, s51
	s_add_i32 s30, 0, 0x14000
	v_add_u32_e32 v142, s29, v177
	v_add_u32_e32 v168, s30, v177
	ds_read_b128 v[130:133], v142
	ds_read_b128 v[134:137], v142 offset:1024
	ds_read_b128 v[138:141], v142 offset:2048
	ds_read_b128 v[142:145], v142 offset:3072
	ds_read_b128 v[146:149], v168
	ds_read_b128 v[150:153], v168 offset:1024
	ds_read_b128 v[164:167], v168 offset:2048
	ds_read_b128 v[168:171], v168 offset:3072
	s_add_i32 m0, s43, 0xc000
	ds_read_b128 v[172:175], v181
	ds_read_b128 v[182:185], v181 offset:1024
	ds_read_b128 v[186:189], v181 offset:2048
	ds_read_b128 v[190:193], v181 offset:3072
	ds_read_b128 v[204:207], v181 offset:4096
	ds_read_b128 v[208:211], v181 offset:5120
	ds_read_b128 v[212:215], v181 offset:6144
	ds_read_b128 v[216:219], v181 offset:7168
	global_load_lds_dwordx4 v162, s[92:93]
	s_add_i32 m0, s43, 0xe000
	s_nop 0
	global_load_lds_dwordx4 v160, s[92:93]
	s_waitcnt vmcnt(8) lgkmcnt(0)
	s_setprio 1
	s_barrier
	v_mfma_f32_16x16x32_bf16 v[126:129], v[130:133], v[172:175], v[126:129]
	v_mfma_f32_16x16x32_bf16 v[122:125], v[138:141], v[172:175], v[122:125]
	v_mfma_f32_16x16x32_bf16 v[110:113], v[130:133], v[186:189], v[110:113]
	v_mfma_f32_16x16x32_bf16 v[106:109], v[138:141], v[186:189], v[106:109]
	v_mfma_f32_16x16x32_bf16 v[94:97], v[130:133], v[204:207], v[94:97]
	v_mfma_f32_16x16x32_bf16 v[90:93], v[138:141], v[204:207], v[90:93]
	v_mfma_f32_16x16x32_bf16 v[78:81], v[130:133], v[212:215], v[78:81]
	v_mfma_f32_16x16x32_bf16 v[74:77], v[138:141], v[212:215], v[74:77]
	v_mfma_f32_16x16x32_bf16 v[126:129], v[134:137], v[182:185], v[126:129]
	v_mfma_f32_16x16x32_bf16 v[122:125], v[142:145], v[182:185], v[122:125]
	v_mfma_f32_16x16x32_bf16 v[110:113], v[134:137], v[190:193], v[110:113]
	v_mfma_f32_16x16x32_bf16 v[106:109], v[142:145], v[190:193], v[106:109]
	v_mfma_f32_16x16x32_bf16 v[94:97], v[134:137], v[208:211], v[94:97]
	v_mfma_f32_16x16x32_bf16 v[90:93], v[142:145], v[208:211], v[90:93]
	v_mfma_f32_16x16x32_bf16 v[78:81], v[134:137], v[216:219], v[78:81]
	v_mfma_f32_16x16x32_bf16 v[74:77], v[142:145], v[216:219], v[74:77]
	s_setprio 0
	s_setprio 1
	v_mfma_f32_16x16x32_bf16 v[118:121], v[146:149], v[172:175], v[118:121]
	v_mfma_f32_16x16x32_bf16 v[114:117], v[164:167], v[172:175], v[114:117]
	v_mfma_f32_16x16x32_bf16 v[102:105], v[146:149], v[186:189], v[102:105]
	v_mfma_f32_16x16x32_bf16 v[98:101], v[164:167], v[186:189], v[98:101]
	v_mfma_f32_16x16x32_bf16 v[86:89], v[146:149], v[204:207], v[86:89]
	v_mfma_f32_16x16x32_bf16 v[82:85], v[164:167], v[204:207], v[82:85]
	v_mfma_f32_16x16x32_bf16 v[70:73], v[146:149], v[212:215], v[70:73]
	v_mfma_f32_16x16x32_bf16 v[66:69], v[164:167], v[212:215], v[66:69]
	v_mfma_f32_16x16x32_bf16 v[118:121], v[150:153], v[182:185], v[118:121]
	v_mfma_f32_16x16x32_bf16 v[114:117], v[168:171], v[182:185], v[114:117]
	v_mfma_f32_16x16x32_bf16 v[102:105], v[150:153], v[190:193], v[102:105]
	v_mfma_f32_16x16x32_bf16 v[98:101], v[168:171], v[190:193], v[98:101]
	v_mfma_f32_16x16x32_bf16 v[86:89], v[150:153], v[208:211], v[86:89]
	v_mfma_f32_16x16x32_bf16 v[82:85], v[168:171], v[208:211], v[82:85]
	v_mfma_f32_16x16x32_bf16 v[70:73], v[150:153], v[216:219], v[70:73]
	v_mfma_f32_16x16x32_bf16 v[66:69], v[168:171], v[216:219], v[66:69]
	s_barrier
	s_setprio 0
	s_add_i32 s29, s29, s15
	s_mov_b32 m0, s29
	ds_read_b128 v[172:175], v181 offset:16384
	ds_read_b128 v[182:185], v181 offset:17408
	ds_read_b128 v[186:189], v181 offset:18432
	ds_read_b128 v[190:193], v181 offset:19456
	ds_read_b128 v[204:207], v181 offset:20480
	ds_read_b128 v[208:211], v181 offset:21504
	ds_read_b128 v[212:215], v181 offset:22528
	ds_read_b128 v[216:219], v181 offset:23552
	global_load_lds_dwordx4 v0, s[20:21]
	s_add_i32 m0, s29, 0x2000
	s_add_u32 s54, s20, 0x40000
	s_addc_u32 s55, s21, 0
	s_add_i32 s29, s30, s15
	global_load_lds_dwordx4 v158, s[20:21]
	s_mov_b32 m0, s29
	s_nop 0
	global_load_lds_dwordx4 v0, s[54:55]
	s_add_i32 m0, s29, 0x2000
	s_nop 0
	global_load_lds_dwordx4 v158, s[54:55]
	s_mov_b32 m0, s43
	s_nop 0
	global_load_lds_dwordx4 v154, s[72:73]
	s_mov_b32 m0, s44
	s_nop 0
	global_load_lds_dwordx4 v156, s[72:73]
	s_waitcnt vmcnt(8) lgkmcnt(0)
	s_setprio 1
	s_barrier
	v_mfma_f32_16x16x32_bf16 v[62:65], v[130:133], v[172:175], v[62:65]
	v_mfma_f32_16x16x32_bf16 v[58:61], v[138:141], v[172:175], v[58:61]
	v_mfma_f32_16x16x32_bf16 v[46:49], v[130:133], v[186:189], v[46:49]
	v_mfma_f32_16x16x32_bf16 v[42:45], v[138:141], v[186:189], v[42:45]
	v_mfma_f32_16x16x32_bf16 v[30:33], v[130:133], v[204:207], v[30:33]
	v_mfma_f32_16x16x32_bf16 v[26:29], v[138:141], v[204:207], v[26:29]
	v_mfma_f32_16x16x32_bf16 v[14:17], v[130:133], v[212:215], v[14:17]
	v_mfma_f32_16x16x32_bf16 v[10:13], v[138:141], v[212:215], v[10:13]
	v_mfma_f32_16x16x32_bf16 v[62:65], v[134:137], v[182:185], v[62:65]
	v_mfma_f32_16x16x32_bf16 v[58:61], v[142:145], v[182:185], v[58:61]
	v_mfma_f32_16x16x32_bf16 v[46:49], v[134:137], v[190:193], v[46:49]
	v_mfma_f32_16x16x32_bf16 v[42:45], v[142:145], v[190:193], v[42:45]
	v_mfma_f32_16x16x32_bf16 v[30:33], v[134:137], v[208:211], v[30:33]
	v_mfma_f32_16x16x32_bf16 v[26:29], v[142:145], v[208:211], v[26:29]
	v_mfma_f32_16x16x32_bf16 v[14:17], v[134:137], v[216:219], v[14:17]
	v_mfma_f32_16x16x32_bf16 v[10:13], v[142:145], v[216:219], v[10:13]
	s_setprio 0
	s_setprio 1
	v_mfma_f32_16x16x32_bf16 v[54:57], v[146:149], v[172:175], v[54:57]
	v_mfma_f32_16x16x32_bf16 v[50:53], v[164:167], v[172:175], v[50:53]
	v_mfma_f32_16x16x32_bf16 v[38:41], v[146:149], v[186:189], v[38:41]
	v_mfma_f32_16x16x32_bf16 v[34:37], v[164:167], v[186:189], v[34:37]
	v_mfma_f32_16x16x32_bf16 v[22:25], v[146:149], v[204:207], v[22:25]
	v_mfma_f32_16x16x32_bf16 v[18:21], v[164:167], v[204:207], v[18:21]
	v_mfma_f32_16x16x32_bf16 v[6:9], v[146:149], v[212:215], v[6:9]
	v_mfma_f32_16x16x32_bf16 v[2:5], v[164:167], v[212:215], v[2:5]
	v_mfma_f32_16x16x32_bf16 v[54:57], v[150:153], v[182:185], v[54:57]
	v_mfma_f32_16x16x32_bf16 v[50:53], v[168:171], v[182:185], v[50:53]
	v_mfma_f32_16x16x32_bf16 v[38:41], v[150:153], v[190:193], v[38:41]
	v_mfma_f32_16x16x32_bf16 v[34:37], v[168:171], v[190:193], v[34:37]
	v_mfma_f32_16x16x32_bf16 v[22:25], v[150:153], v[208:211], v[22:25]
	v_mfma_f32_16x16x32_bf16 v[18:21], v[168:171], v[208:211], v[18:21]
	v_mfma_f32_16x16x32_bf16 v[6:9], v[150:153], v[216:219], v[6:9]
	v_mfma_f32_16x16x32_bf16 v[2:5], v[168:171], v[216:219], v[2:5]
	s_barrier
; #define PG8_STAGE(bufoff, gbase, voff) do { _Pragma("unroll") for (int _i = 0; _i < 2; ++_i) \
;         __builtin_amdgcn_global_load_lds((const gunsigned*)((const gchar*)(gbase) + (voff)[_i]), (LAS unsigned*)(lds + (bufoff) + ldsw + _i * 8192), 16, 0, 0); } while (0)
; #define PG8_LDA(dst, b, h) do { _Pragma("unroll") for (int m = 0; m < 4; ++m) _Pragma("unroll") for (int k = 0; k < 2; ++k) dst[m][k] = *(const LAS bf16x8*)(lds + PG8_SA(b, h) + aoff + m * 2048 + k * 1024); } while (0)
; #define PG8_LDB(dst, b, h) do { _Pragma("unroll") for (int n = 0; n < 2; ++n) _Pragma("unroll") for (int k = 0; k < 2; ++k) dst[n][k] = *(const LAS bf16x8*)(lds + PG8_SB(b, h) + boff + n * 2048 + k * 1024); } while (0)
; #define PG8_MMA(ai, bj, At, Bt) do { __builtin_amdgcn_s_setprio(1); _Pragma("unroll") for (int m = 0; m < 4; ++m) _Pragma("unroll") for (int n = 0; n < 2; ++n) _Pragma("unroll") for (int k = 0; k < 2; ++k) \
;         acc[ai][bj][m][n] = __builtin_amdgcn_mfma_f32_16x16x32_bf16(Bt[n][k], At[m][k], acc[ai][bj][m][n], 0, 0, 0); __builtin_amdgcn_s_setprio(0); } while (0)
; #define PG8_WAIT_V(n) asm volatile("s_waitcnt vmcnt(" #n ")" ::: "memory")
; #define PG8_WAIT_L(n) asm volatile("s_waitcnt lgkmcnt(" #n ")" ::: "memory")
; #define PG8_BAR __builtin_amdgcn_s_barrier()
; #define PG8_SCHED __builtin_amdgcn_sched_barrier(0)
; template <class Epi, class Sched>
; __device__ __forceinline__ void gemm_phase(LAS unsigned char* lds, const int tid, const Gemm g, const Sched& S, const Epi& E) {
;     ...
;             PG8_LDB(B0, 1, 0); PG8_LDB(B1, 1, 1); PG8_SCHED; PG8_LDA(At, 1, 0); PG8_STAGE(PG8_SA(0, 1), a2 + hstep, voffA);
;             PG8_WAIT_V(8); PG8_WAIT_L(0); PG8_BAR; PG8_MMA(0, 0, At, B0); PG8_MMA(0, 1, At, B1); PG8_BAR; PG8_SCHED;
;             PG8_LDA(At, 1, 1); PG8_STAGE(PG8_SB(1, 0), b3, voffB); PG8_STAGE(PG8_SB(1, 1), b3 + hstep, voffB); PG8_STAGE(PG8_SA(1, 0), a3, voffA);
;             PG8_WAIT_V(8); PG8_WAIT_L(0); PG8_BAR; PG8_MMA(1, 0, At, B0); PG8_MMA(1, 1, At, B1); PG8_BAR; PG8_SCHED;
;         }
;         if (wr == 0) PG8_BAR;
	s_setprio 0
	s_add_i32 s29, 0, 0x18000
	s_add_i32 s30, 0, 0x1c000
	v_add_u32_e32 v142, s29, v177
	v_add_u32_e32 v168, s30, v177
	ds_read_b128 v[130:133], v142
	ds_read_b128 v[134:137], v142 offset:1024
	ds_read_b128 v[138:141], v142 offset:2048
	ds_read_b128 v[142:145], v142 offset:3072
	ds_read_b128 v[146:149], v168
	ds_read_b128 v[150:153], v168 offset:1024
	ds_read_b128 v[164:167], v168 offset:2048
	ds_read_b128 v[168:171], v168 offset:3072
	s_add_u32 s54, s72, 0x40000
	s_addc_u32 s55, s73, 0
	s_mov_b32 m0, s45
	ds_read_b128 v[172:175], v181 offset:32768
	ds_read_b128 v[182:185], v181 offset:33792
	ds_read_b128 v[186:189], v181 offset:34816
	ds_read_b128 v[190:193], v181 offset:35840
	ds_read_b128 v[204:207], v181 offset:36864
	ds_read_b128 v[208:211], v181 offset:37888
	ds_read_b128 v[212:215], v181 offset:38912
	ds_read_b128 v[216:219], v181 offset:39936
	global_load_lds_dwordx4 v154, s[54:55]
	s_mov_b32 m0, s46
	s_nop 0
	global_load_lds_dwordx4 v156, s[54:55]
	s_waitcnt vmcnt(8) lgkmcnt(0)
	s_setprio 1
	s_barrier
	v_mfma_f32_16x16x32_bf16 v[126:129], v[130:133], v[172:175], v[126:129]
	v_mfma_f32_16x16x32_bf16 v[122:125], v[138:141], v[172:175], v[122:125]
	v_mfma_f32_16x16x32_bf16 v[110:113], v[130:133], v[186:189], v[110:113]
	v_mfma_f32_16x16x32_bf16 v[106:109], v[138:141], v[186:189], v[106:109]
	v_mfma_f32_16x16x32_bf16 v[94:97], v[130:133], v[204:207], v[94:97]
	v_mfma_f32_16x16x32_bf16 v[90:93], v[138:141], v[204:207], v[90:93]
	v_mfma_f32_16x16x32_bf16 v[78:81], v[130:133], v[212:215], v[78:81]
	v_mfma_f32_16x16x32_bf16 v[74:77], v[138:141], v[212:215], v[74:77]
	v_mfma_f32_16x16x32_bf16 v[126:129], v[134:137], v[182:185], v[126:129]
	v_mfma_f32_16x16x32_bf16 v[122:125], v[142:145], v[182:185], v[122:125]
	v_mfma_f32_16x16x32_bf16 v[110:113], v[134:137], v[190:193], v[110:113]
	v_mfma_f32_16x16x32_bf16 v[106:109], v[142:145], v[190:193], v[106:109]
	v_mfma_f32_16x16x32_bf16 v[94:97], v[134:137], v[208:211], v[94:97]
	v_mfma_f32_16x16x32_bf16 v[90:93], v[142:145], v[208:211], v[90:93]
	v_mfma_f32_16x16x32_bf16 v[78:81], v[134:137], v[216:219], v[78:81]
	v_mfma_f32_16x16x32_bf16 v[74:77], v[142:145], v[216:219], v[74:77]
	s_setprio 0
	s_setprio 1
	v_mfma_f32_16x16x32_bf16 v[118:121], v[146:149], v[172:175], v[118:121]
	v_mfma_f32_16x16x32_bf16 v[114:117], v[164:167], v[172:175], v[114:117]
	v_mfma_f32_16x16x32_bf16 v[102:105], v[146:149], v[186:189], v[102:105]
	v_mfma_f32_16x16x32_bf16 v[98:101], v[164:167], v[186:189], v[98:101]
	v_mfma_f32_16x16x32_bf16 v[86:89], v[146:149], v[204:207], v[86:89]
	v_mfma_f32_16x16x32_bf16 v[82:85], v[164:167], v[204:207], v[82:85]
	v_mfma_f32_16x16x32_bf16 v[70:73], v[146:149], v[212:215], v[70:73]
	v_mfma_f32_16x16x32_bf16 v[66:69], v[164:167], v[212:215], v[66:69]
	v_mfma_f32_16x16x32_bf16 v[118:121], v[150:153], v[182:185], v[118:121]
	v_mfma_f32_16x16x32_bf16 v[114:117], v[168:171], v[182:185], v[114:117]
	v_mfma_f32_16x16x32_bf16 v[102:105], v[150:153], v[190:193], v[102:105]
	v_mfma_f32_16x16x32_bf16 v[98:101], v[168:171], v[190:193], v[98:101]
	v_mfma_f32_16x16x32_bf16 v[86:89], v[150:153], v[208:211], v[86:89]
	v_mfma_f32_16x16x32_bf16 v[82:85], v[168:171], v[208:211], v[82:85]
	v_mfma_f32_16x16x32_bf16 v[70:73], v[150:153], v[216:219], v[70:73]
	v_mfma_f32_16x16x32_bf16 v[66:69], v[168:171], v[216:219], v[66:69]
	s_barrier
	s_setprio 0
	s_add_i32 s29, s29, s15
	s_mov_b32 m0, s29
	ds_read_b128 v[172:175], v181 offset:49152
	ds_read_b128 v[182:185], v181 offset:50176
	ds_read_b128 v[186:189], v181 offset:51200
	ds_read_b128 v[190:193], v181 offset:52224
	ds_read_b128 v[204:207], v181 offset:53248
	ds_read_b128 v[208:211], v181 offset:54272
	ds_read_b128 v[212:215], v181 offset:55296
	ds_read_b128 v[216:219], v181 offset:56320
	global_load_lds_dwordx4 v195, s[20:21]
	s_add_i32 m0, s29, 0x2000
	s_add_i32 s29, s30, s15
	global_load_lds_dwordx4 v201, s[20:21]
	s_add_u32 s20, s20, 0x40080
	s_addc_u32 s21, s21, 0
	s_mov_b32 m0, s29
	s_nop 0
	global_load_lds_dwordx4 v0, s[20:21]
	s_add_i32 m0, s29, 0x2000
	s_nop 0
	global_load_lds_dwordx4 v158, s[20:21]
	s_mov_b32 m0, s12
	s_nop 0
	global_load_lds_dwordx4 v221, s[72:73]
	s_mov_b32 m0, s47
	s_nop 0
	global_load_lds_dwordx4 v223, s[72:73]
	s_waitcnt vmcnt(8) lgkmcnt(0)
	s_setprio 1
	s_barrier
	v_mfma_f32_16x16x32_bf16 v[62:65], v[130:133], v[172:175], v[62:65]
	v_mfma_f32_16x16x32_bf16 v[58:61], v[138:141], v[172:175], v[58:61]
	v_mfma_f32_16x16x32_bf16 v[46:49], v[130:133], v[186:189], v[46:49]
	v_mfma_f32_16x16x32_bf16 v[42:45], v[138:141], v[186:189], v[42:45]
	v_mfma_f32_16x16x32_bf16 v[30:33], v[130:133], v[204:207], v[30:33]
	v_mfma_f32_16x16x32_bf16 v[26:29], v[138:141], v[204:207], v[26:29]
	v_mfma_f32_16x16x32_bf16 v[14:17], v[130:133], v[212:215], v[14:17]
	v_mfma_f32_16x16x32_bf16 v[10:13], v[138:141], v[212:215], v[10:13]
	v_mfma_f32_16x16x32_bf16 v[62:65], v[134:137], v[182:185], v[62:65]
	v_mfma_f32_16x16x32_bf16 v[58:61], v[142:145], v[182:185], v[58:61]
	v_mfma_f32_16x16x32_bf16 v[46:49], v[134:137], v[190:193], v[46:49]
	v_mfma_f32_16x16x32_bf16 v[42:45], v[142:145], v[190:193], v[42:45]
	v_mfma_f32_16x16x32_bf16 v[30:33], v[134:137], v[208:211], v[30:33]
	v_mfma_f32_16x16x32_bf16 v[26:29], v[142:145], v[208:211], v[26:29]
	v_mfma_f32_16x16x32_bf16 v[14:17], v[134:137], v[216:219], v[14:17]
	v_mfma_f32_16x16x32_bf16 v[10:13], v[142:145], v[216:219], v[10:13]
	s_setprio 0
	s_setprio 1
	v_mfma_f32_16x16x32_bf16 v[54:57], v[146:149], v[172:175], v[54:57]
	v_mfma_f32_16x16x32_bf16 v[50:53], v[164:167], v[172:175], v[50:53]
	v_mfma_f32_16x16x32_bf16 v[38:41], v[146:149], v[186:189], v[38:41]
	v_mfma_f32_16x16x32_bf16 v[34:37], v[164:167], v[186:189], v[34:37]
	v_mfma_f32_16x16x32_bf16 v[22:25], v[146:149], v[204:207], v[22:25]
	v_mfma_f32_16x16x32_bf16 v[18:21], v[164:167], v[204:207], v[18:21]
	v_mfma_f32_16x16x32_bf16 v[6:9], v[146:149], v[212:215], v[6:9]
	v_mfma_f32_16x16x32_bf16 v[2:5], v[164:167], v[212:215], v[2:5]
	v_mfma_f32_16x16x32_bf16 v[54:57], v[150:153], v[182:185], v[54:57]
	v_mfma_f32_16x16x32_bf16 v[50:53], v[168:171], v[182:185], v[50:53]
	v_mfma_f32_16x16x32_bf16 v[38:41], v[150:153], v[190:193], v[38:41]
	v_mfma_f32_16x16x32_bf16 v[34:37], v[168:171], v[190:193], v[34:37]
	v_mfma_f32_16x16x32_bf16 v[22:25], v[150:153], v[208:211], v[22:25]
	v_mfma_f32_16x16x32_bf16 v[18:21], v[168:171], v[208:211], v[18:21]
	v_mfma_f32_16x16x32_bf16 v[6:9], v[150:153], v[216:219], v[6:9]
	v_mfma_f32_16x16x32_bf16 v[2:5], v[168:171], v[216:219], v[2:5]
	s_barrier
	s_setprio 0
	s_add_i32 s53, s53, 2
	s_add_u32 s51, s51, 0x100
	s_addc_u32 s52, s52, 0
	s_add_u32 s92, s92, 0x100
	s_addc_u32 s93, s93, 0
	s_cmp_gt_u32 s53, 13
	s_cbranch_scc0 .LBB0_397
	s_and_b64 vcc, exec, s[10:11]
	s_cbranch_vccz .LBB0_400
	s_barrier

; #define PG8_STAGE(bufoff, gbase, voff) do { _Pragma("unroll") for (int _i = 0; _i < 2; ++_i) \
;         __builtin_amdgcn_global_load_lds((const gunsigned*)((const gchar*)(gbase) + (voff)[_i]), (LAS unsigned*)(lds + (bufoff) + ldsw + _i * 8192), 16, 0, 0); } while (0)
; #define PG8_LDA(dst, b, h) do { _Pragma("unroll") for (int m = 0; m < 4; ++m) _Pragma("unroll") for (int k = 0; k < 2; ++k) dst[m][k] = *(const LAS bf16x8*)(lds + PG8_SA(b, h) + aoff + m * 2048 + k * 1024); } while (0)
; #define PG8_LDB(dst, b, h) do { _Pragma("unroll") for (int n = 0; n < 2; ++n) _Pragma("unroll") for (int k = 0; k < 2; ++k) dst[n][k] = *(const LAS bf16x8*)(lds + PG8_SB(b, h) + boff + n * 2048 + k * 1024); } while (0)
; #define PG8_MMA(ai, bj, At, Bt) do { __builtin_amdgcn_s_setprio(1); _Pragma("unroll") for (int m = 0; m < 4; ++m) _Pragma("unroll") for (int n = 0; n < 2; ++n) _Pragma("unroll") for (int k = 0; k < 2; ++k) \
;         acc[ai][bj][m][n] = __builtin_amdgcn_mfma_f32_16x16x32_bf16(Bt[n][k], At[m][k], acc[ai][bj][m][n], 0, 0, 0); __builtin_amdgcn_s_setprio(0); } while (0)
; #define PG8_WAIT_V(n) asm volatile("s_waitcnt vmcnt(" #n ")" ::: "memory")
; #define PG8_WAIT_L(n) asm volatile("s_waitcnt lgkmcnt(" #n ")" ::: "memory")
; #define PG8_BAR __builtin_amdgcn_s_barrier()
; #define PG8_SCHED __builtin_amdgcn_sched_barrier(0)
; template <class Epi, class Sched>
; __device__ __forceinline__ void gemm_phase(LAS unsigned char* lds, const int tid, const Gemm g, const Sched& S, const Epi& E) {
;     ...
;         for (int t = 0; t < nt; t += 2) {
;             const bool last = (t == nt - 2);
;             const gchar* a1 = cA + (size_t)(t + 1) * kstep;
;             const gchar* a2 = last ? nA : cA + (size_t)(t + 2) * kstep; const gchar* b2 = last ? nB : cB + (size_t)(t + 2) * kstep;
;             const gchar* a3 = a2 + kstep; const gchar* b3 = b2 + kstep;
;             PG8_LDB(B0, 0, 0); PG8_LDB(B1, 0, 1); PG8_SCHED; PG8_LDA(At, 0, 0); PG8_STAGE(PG8_SA(1, 1), a1 + hstep, voffA);
;             PG8_WAIT_V(8); PG8_WAIT_L(0); PG8_BAR; PG8_MMA(0, 0, At, B0); PG8_MMA(0, 1, At, B1); PG8_BAR; PG8_SCHED;
;             PG8_LDA(At, 0, 1); PG8_STAGE(PG8_SB(0, 0), b2, voffB); PG8_STAGE(PG8_SB(0, 1), b2 + hstep, voffB); PG8_STAGE(PG8_SA(0, 0), a2, voffA);
;             PG8_WAIT_V(8); PG8_WAIT_L(0); PG8_BAR; PG8_MMA(1, 0, At, B0); PG8_MMA(1, 1, At, B1); PG8_BAR; PG8_SCHED;
.LBB0_444:
	s_add_u32 s20, s16, 0xfffe0080
	s_addc_u32 s21, s17, -1
	s_add_i32 s29, 0, 0x10000
	s_cmp_eq_u32 s51, 4
	s_cselect_b32 s73, s1, s21
	s_cselect_b32 s72, s5, s20
	v_add_u32_e32 v122, s29, v242
	s_cselect_b32 s21, s15, s31
	s_cselect_b32 s20, s23, s24
	s_add_i32 s30, 0, 0x14000
	ds_read_b128 v[132:135], v122
	ds_read_b128 v[136:139], v122 offset:1024
	ds_read_b128 v[140:143], v122 offset:2048
	ds_read_b128 v[144:147], v122 offset:3072
	v_add_u32_e32 v122, s30, v242
	ds_read_b128 v[148:151], v122
	ds_read_b128 v[152:155], v122 offset:1024
	ds_read_b128 v[156:159], v122 offset:2048
	ds_read_b128 v[160:163], v122 offset:3072
	s_add_i32 m0, s93, 0xc000
	ds_read_b128 v[164:167], v244
	ds_read_b128 v[168:171], v244 offset:1024
	ds_read_b128 v[172:175], v244 offset:2048
	ds_read_b128 v[176:179], v244 offset:3072
	ds_read_b128 v[180:183], v244 offset:4096
	ds_read_b128 v[184:187], v244 offset:5120
	ds_read_b128 v[188:191], v244 offset:6144
	ds_read_b128 v[192:195], v244 offset:7168
	global_load_lds_dwordx4 v212, s[16:17]
	s_add_i32 m0, s93, 0xe000
	s_nop 0
	global_load_lds_dwordx4 v210, s[16:17]
	s_waitcnt vmcnt(8) lgkmcnt(0)
	s_setprio 1
	s_barrier
	v_mfma_f32_16x16x32_bf16 v[128:131], v[132:135], v[164:167], v[128:131]
	v_mfma_f32_16x16x32_bf16 v[122:125], v[140:143], v[164:167], v[124:127]
	v_mfma_f32_16x16x32_bf16 v[110:113], v[132:135], v[172:175], v[110:113]
	v_mfma_f32_16x16x32_bf16 v[106:109], v[140:143], v[172:175], v[106:109]
	v_mfma_f32_16x16x32_bf16 v[94:97], v[132:135], v[180:183], v[94:97]
	v_mfma_f32_16x16x32_bf16 v[90:93], v[140:143], v[180:183], v[90:93]
	v_mfma_f32_16x16x32_bf16 v[78:81], v[132:135], v[188:191], v[78:81]
	v_mfma_f32_16x16x32_bf16 v[74:77], v[140:143], v[188:191], v[74:77]
	v_mfma_f32_16x16x32_bf16 v[128:131], v[136:139], v[168:171], v[128:131]
	v_mfma_f32_16x16x32_bf16 v[122:125], v[144:147], v[168:171], v[122:125]
	v_mfma_f32_16x16x32_bf16 v[110:113], v[136:139], v[176:179], v[110:113]
	v_mfma_f32_16x16x32_bf16 v[106:109], v[144:147], v[176:179], v[106:109]
	v_mfma_f32_16x16x32_bf16 v[94:97], v[136:139], v[184:187], v[94:97]
	v_mfma_f32_16x16x32_bf16 v[90:93], v[144:147], v[184:187], v[90:93]
	v_mfma_f32_16x16x32_bf16 v[78:81], v[136:139], v[192:195], v[78:81]
	v_mfma_f32_16x16x32_bf16 v[74:77], v[144:147], v[192:195], v[74:77]
	s_setprio 0
	s_setprio 1
	v_mfma_f32_16x16x32_bf16 v[118:121], v[148:151], v[164:167], v[118:121]
	v_mfma_f32_16x16x32_bf16 v[114:117], v[156:159], v[164:167], v[114:117]
	v_mfma_f32_16x16x32_bf16 v[102:105], v[148:151], v[172:175], v[102:105]
	v_mfma_f32_16x16x32_bf16 v[98:101], v[156:159], v[172:175], v[98:101]
	v_mfma_f32_16x16x32_bf16 v[86:89], v[148:151], v[180:183], v[86:89]
	v_mfma_f32_16x16x32_bf16 v[82:85], v[156:159], v[180:183], v[82:85]
	v_mfma_f32_16x16x32_bf16 v[70:73], v[148:151], v[188:191], v[70:73]
	v_mfma_f32_16x16x32_bf16 v[66:69], v[156:159], v[188:191], v[66:69]
	v_mfma_f32_16x16x32_bf16 v[118:121], v[152:155], v[168:171], v[118:121]
	v_mfma_f32_16x16x32_bf16 v[114:117], v[160:163], v[168:171], v[114:117]
	v_mfma_f32_16x16x32_bf16 v[102:105], v[152:155], v[176:179], v[102:105]
	v_mfma_f32_16x16x32_bf16 v[98:101], v[160:163], v[176:179], v[98:101]
	v_mfma_f32_16x16x32_bf16 v[86:89], v[152:155], v[184:187], v[86:89]
	v_mfma_f32_16x16x32_bf16 v[82:85], v[160:163], v[184:187], v[82:85]
	v_mfma_f32_16x16x32_bf16 v[70:73], v[152:155], v[192:195], v[70:73]
	v_mfma_f32_16x16x32_bf16 v[66:69], v[160:163], v[192:195], v[66:69]
	s_barrier
	s_setprio 0
	s_add_i32 s29, s29, s42
	s_mov_b32 m0, s29
	ds_read_b128 v[164:167], v244 offset:16384
	ds_read_b128 v[168:171], v244 offset:17408
	ds_read_b128 v[172:175], v244 offset:18432
	ds_read_b128 v[176:179], v244 offset:19456
	ds_read_b128 v[180:183], v244 offset:20480
	ds_read_b128 v[184:187], v244 offset:21504
	ds_read_b128 v[188:191], v244 offset:22528
	ds_read_b128 v[192:195], v244 offset:23552
	global_load_lds_dwordx4 v0, s[20:21]
	s_add_i32 m0, s29, 0x2000
	s_add_u32 s52, s20, 0x20000
	s_addc_u32 s53, s21, 0
	s_add_i32 s29, s30, s42
	global_load_lds_dwordx4 v208, s[20:21]
	s_mov_b32 m0, s29
	s_nop 0
	global_load_lds_dwordx4 v0, s[52:53]
	s_add_i32 m0, s29, 0x2000
	s_nop 0
	global_load_lds_dwordx4 v208, s[52:53]
	s_mov_b32 m0, s93
	s_nop 0
	global_load_lds_dwordx4 v204, s[72:73]
	s_mov_b32 m0, s44
	s_nop 0
	global_load_lds_dwordx4 v206, s[72:73]
	s_waitcnt vmcnt(8) lgkmcnt(0)
	s_setprio 1
	s_barrier
	v_mfma_f32_16x16x32_bf16 v[62:65], v[132:135], v[164:167], v[62:65]
	v_mfma_f32_16x16x32_bf16 v[58:61], v[140:143], v[164:167], v[58:61]
	v_mfma_f32_16x16x32_bf16 v[46:49], v[132:135], v[172:175], v[46:49]
	v_mfma_f32_16x16x32_bf16 v[42:45], v[140:143], v[172:175], v[42:45]
	v_mfma_f32_16x16x32_bf16 v[30:33], v[132:135], v[180:183], v[30:33]
	v_mfma_f32_16x16x32_bf16 v[26:29], v[140:143], v[180:183], v[26:29]
	v_mfma_f32_16x16x32_bf16 v[14:17], v[132:135], v[188:191], v[14:17]
	v_mfma_f32_16x16x32_bf16 v[10:13], v[140:143], v[188:191], v[10:13]
	v_mfma_f32_16x16x32_bf16 v[62:65], v[136:139], v[168:171], v[62:65]
	v_mfma_f32_16x16x32_bf16 v[58:61], v[144:147], v[168:171], v[58:61]
	v_mfma_f32_16x16x32_bf16 v[46:49], v[136:139], v[176:179], v[46:49]
	v_mfma_f32_16x16x32_bf16 v[42:45], v[144:147], v[176:179], v[42:45]
	v_mfma_f32_16x16x32_bf16 v[30:33], v[136:139], v[184:187], v[30:33]
	v_mfma_f32_16x16x32_bf16 v[26:29], v[144:147], v[184:187], v[26:29]
	v_mfma_f32_16x16x32_bf16 v[14:17], v[136:139], v[192:195], v[14:17]
	v_mfma_f32_16x16x32_bf16 v[10:13], v[144:147], v[192:195], v[10:13]
	s_setprio 0
	s_setprio 1
	v_mfma_f32_16x16x32_bf16 v[54:57], v[148:151], v[164:167], v[54:57]
	v_mfma_f32_16x16x32_bf16 v[50:53], v[156:159], v[164:167], v[50:53]
	v_mfma_f32_16x16x32_bf16 v[38:41], v[148:151], v[172:175], v[38:41]
	v_mfma_f32_16x16x32_bf16 v[34:37], v[156:159], v[172:175], v[34:37]
	v_mfma_f32_16x16x32_bf16 v[22:25], v[148:151], v[180:183], v[22:25]
	v_mfma_f32_16x16x32_bf16 v[18:21], v[156:159], v[180:183], v[18:21]
	v_mfma_f32_16x16x32_bf16 v[6:9], v[148:151], v[188:191], v[6:9]
	v_mfma_f32_16x16x32_bf16 v[2:5], v[156:159], v[188:191], v[2:5]
	v_mfma_f32_16x16x32_bf16 v[54:57], v[152:155], v[168:171], v[54:57]
	v_mfma_f32_16x16x32_bf16 v[50:53], v[160:163], v[168:171], v[50:53]
	v_mfma_f32_16x16x32_bf16 v[38:41], v[152:155], v[176:179], v[38:41]
	v_mfma_f32_16x16x32_bf16 v[34:37], v[160:163], v[176:179], v[34:37]
	v_mfma_f32_16x16x32_bf16 v[22:25], v[152:155], v[184:187], v[22:25]
	v_mfma_f32_16x16x32_bf16 v[18:21], v[160:163], v[184:187], v[18:21]
	v_mfma_f32_16x16x32_bf16 v[6:9], v[152:155], v[192:195], v[6:9]
	v_mfma_f32_16x16x32_bf16 v[2:5], v[160:163], v[192:195], v[2:5]
	s_barrier
; #define PG8_STAGE(bufoff, gbase, voff) do { _Pragma("unroll") for (int _i = 0; _i < 2; ++_i) \
;         __builtin_amdgcn_global_load_lds((const gunsigned*)((const gchar*)(gbase) + (voff)[_i]), (LAS unsigned*)(lds + (bufoff) + ldsw + _i * 8192), 16, 0, 0); } while (0)
; #define PG8_LDA(dst, b, h) do { _Pragma("unroll") for (int m = 0; m < 4; ++m) _Pragma("unroll") for (int k = 0; k < 2; ++k) dst[m][k] = *(const LAS bf16x8*)(lds + PG8_SA(b, h) + aoff + m * 2048 + k * 1024); } while (0)
; #define PG8_LDB(dst, b, h) do { _Pragma("unroll") for (int n = 0; n < 2; ++n) _Pragma("unroll") for (int k = 0; k < 2; ++k) dst[n][k] = *(const LAS bf16x8*)(lds + PG8_SB(b, h) + boff + n * 2048 + k * 1024); } while (0)
; #define PG8_MMA(ai, bj, At, Bt) do { __builtin_amdgcn_s_setprio(1); _Pragma("unroll") for (int m = 0; m < 4; ++m) _Pragma("unroll") for (int n = 0; n < 2; ++n) _Pragma("unroll") for (int k = 0; k < 2; ++k) \
;         acc[ai][bj][m][n] = __builtin_amdgcn_mfma_f32_16x16x32_bf16(Bt[n][k], At[m][k], acc[ai][bj][m][n], 0, 0, 0); __builtin_amdgcn_s_setprio(0); } while (0)
; #define PG8_WAIT_V(n) asm volatile("s_waitcnt vmcnt(" #n ")" ::: "memory")
; #define PG8_WAIT_L(n) asm volatile("s_waitcnt lgkmcnt(" #n ")" ::: "memory")
; #define PG8_BAR __builtin_amdgcn_s_barrier()
; #define PG8_SCHED __builtin_amdgcn_sched_barrier(0)
; template <class Epi, class Sched>
; __device__ __forceinline__ void gemm_phase(LAS unsigned char* lds, const int tid, const Gemm g, const Sched& S, const Epi& E) {
;     ...
;             PG8_LDB(B0, 1, 0); PG8_LDB(B1, 1, 1); PG8_SCHED; PG8_LDA(At, 1, 0); PG8_STAGE(PG8_SA(0, 1), a2 + hstep, voffA);
;             PG8_WAIT_V(8); PG8_WAIT_L(0); PG8_BAR; PG8_MMA(0, 0, At, B0); PG8_MMA(0, 1, At, B1); PG8_BAR; PG8_SCHED;
;             PG8_LDA(At, 1, 1); PG8_STAGE(PG8_SB(1, 0), b3, voffB); PG8_STAGE(PG8_SB(1, 1), b3 + hstep, voffB); PG8_STAGE(PG8_SA(1, 0), a3, voffA);
;             PG8_WAIT_V(8); PG8_WAIT_L(0); PG8_BAR; PG8_MMA(1, 0, At, B0); PG8_MMA(1, 1, At, B1); PG8_BAR; PG8_SCHED;
;         }
;         if (wr == 0) PG8_BAR;
	s_setprio 0
	s_add_i32 s29, 0, 0x18000
	v_add_u32_e32 v126, s29, v242
	s_add_i32 s30, 0, 0x1c000
	ds_read_b128 v[132:135], v126
	ds_read_b128 v[136:139], v126 offset:1024
	ds_read_b128 v[140:143], v126 offset:2048
	ds_read_b128 v[144:147], v126 offset:3072
	v_add_u32_e32 v126, s30, v242
	ds_read_b128 v[148:151], v126
	ds_read_b128 v[152:155], v126 offset:1024
	ds_read_b128 v[156:159], v126 offset:2048
	ds_read_b128 v[160:163], v126 offset:3072
	s_add_u32 s52, s72, 0x20000
	s_addc_u32 s53, s73, 0
	s_mov_b32 m0, s45
	ds_read_b128 v[164:167], v244 offset:32768
	ds_read_b128 v[168:171], v244 offset:33792
	ds_read_b128 v[172:175], v244 offset:34816
	ds_read_b128 v[176:179], v244 offset:35840
	ds_read_b128 v[180:183], v244 offset:36864
	ds_read_b128 v[184:187], v244 offset:37888
	ds_read_b128 v[188:191], v244 offset:38912
	ds_read_b128 v[192:195], v244 offset:39936
	global_load_lds_dwordx4 v204, s[52:53]
	s_mov_b32 m0, s46
	s_nop 0
	global_load_lds_dwordx4 v206, s[52:53]
	s_waitcnt vmcnt(8) lgkmcnt(0)
	s_setprio 1
	s_barrier
	v_mfma_f32_16x16x32_bf16 v[126:129], v[132:135], v[164:167], v[128:131]
	v_mfma_f32_16x16x32_bf16 v[122:125], v[140:143], v[164:167], v[122:125]
	v_mfma_f32_16x16x32_bf16 v[110:113], v[132:135], v[172:175], v[110:113]
	v_mfma_f32_16x16x32_bf16 v[106:109], v[140:143], v[172:175], v[106:109]
	v_mfma_f32_16x16x32_bf16 v[94:97], v[132:135], v[180:183], v[94:97]
	v_mfma_f32_16x16x32_bf16 v[90:93], v[140:143], v[180:183], v[90:93]
	v_mfma_f32_16x16x32_bf16 v[78:81], v[132:135], v[188:191], v[78:81]
	v_mfma_f32_16x16x32_bf16 v[74:77], v[140:143], v[188:191], v[74:77]
	v_mfma_f32_16x16x32_bf16 v[128:131], v[136:139], v[168:171], v[126:129]
	v_mfma_f32_16x16x32_bf16 v[124:127], v[144:147], v[168:171], v[122:125]
	v_mfma_f32_16x16x32_bf16 v[110:113], v[136:139], v[176:179], v[110:113]
	v_mfma_f32_16x16x32_bf16 v[106:109], v[144:147], v[176:179], v[106:109]
	v_mfma_f32_16x16x32_bf16 v[94:97], v[136:139], v[184:187], v[94:97]
	v_mfma_f32_16x16x32_bf16 v[90:93], v[144:147], v[184:187], v[90:93]
	v_mfma_f32_16x16x32_bf16 v[78:81], v[136:139], v[192:195], v[78:81]
	v_mfma_f32_16x16x32_bf16 v[74:77], v[144:147], v[192:195], v[74:77]
	s_setprio 0
	s_setprio 1
	v_mfma_f32_16x16x32_bf16 v[118:121], v[148:151], v[164:167], v[118:121]
	v_mfma_f32_16x16x32_bf16 v[114:117], v[156:159], v[164:167], v[114:117]
	v_mfma_f32_16x16x32_bf16 v[102:105], v[148:151], v[172:175], v[102:105]
	v_mfma_f32_16x16x32_bf16 v[98:101], v[156:159], v[172:175], v[98:101]
	v_mfma_f32_16x16x32_bf16 v[86:89], v[148:151], v[180:183], v[86:89]
	v_mfma_f32_16x16x32_bf16 v[82:85], v[156:159], v[180:183], v[82:85]
	v_mfma_f32_16x16x32_bf16 v[70:73], v[148:151], v[188:191], v[70:73]
	v_mfma_f32_16x16x32_bf16 v[66:69], v[156:159], v[188:191], v[66:69]
	v_mfma_f32_16x16x32_bf16 v[118:121], v[152:155], v[168:171], v[118:121]
	v_mfma_f32_16x16x32_bf16 v[114:117], v[160:163], v[168:171], v[114:117]
	v_mfma_f32_16x16x32_bf16 v[102:105], v[152:155], v[176:179], v[102:105]
	v_mfma_f32_16x16x32_bf16 v[98:101], v[160:163], v[176:179], v[98:101]
	v_mfma_f32_16x16x32_bf16 v[86:89], v[152:155], v[184:187], v[86:89]
	v_mfma_f32_16x16x32_bf16 v[82:85], v[160:163], v[184:187], v[82:85]
	v_mfma_f32_16x16x32_bf16 v[70:73], v[152:155], v[192:195], v[70:73]
	v_mfma_f32_16x16x32_bf16 v[66:69], v[160:163], v[192:195], v[66:69]
	s_barrier
	s_setprio 0
	s_add_i32 s29, s29, s42
	s_mov_b32 m0, s29
	ds_read_b128 v[164:167], v244 offset:49152
	ds_read_b128 v[168:171], v244 offset:50176
	ds_read_b128 v[172:175], v244 offset:51200
	ds_read_b128 v[176:179], v244 offset:52224
	ds_read_b128 v[180:183], v244 offset:53248
	ds_read_b128 v[184:187], v244 offset:54272
	ds_read_b128 v[188:191], v244 offset:55296
	ds_read_b128 v[192:195], v244 offset:56320
	global_load_lds_dwordx4 v201, s[20:21]
	s_add_i32 m0, s29, 0x2000
	s_add_i32 s29, s30, s42
	global_load_lds_dwordx4 v215, s[20:21]
	s_add_u32 s20, s20, 0x20080
	s_addc_u32 s21, s21, 0
	s_mov_b32 m0, s29
	s_nop 0
	global_load_lds_dwordx4 v0, s[20:21]
	s_add_i32 m0, s29, 0x2000
	s_nop 0
	global_load_lds_dwordx4 v208, s[20:21]
	s_mov_b32 m0, s47
	s_nop 0
	global_load_lds_dwordx4 v217, s[72:73]
	s_mov_b32 m0, s48
	s_nop 0
	global_load_lds_dwordx4 v219, s[72:73]
	s_waitcnt vmcnt(8) lgkmcnt(0)
	s_setprio 1
	s_barrier
	v_mfma_f32_16x16x32_bf16 v[62:65], v[132:135], v[164:167], v[62:65]
	v_mfma_f32_16x16x32_bf16 v[58:61], v[140:143], v[164:167], v[58:61]
	v_mfma_f32_16x16x32_bf16 v[46:49], v[132:135], v[172:175], v[46:49]
	v_mfma_f32_16x16x32_bf16 v[42:45], v[140:143], v[172:175], v[42:45]
	v_mfma_f32_16x16x32_bf16 v[30:33], v[132:135], v[180:183], v[30:33]
	v_mfma_f32_16x16x32_bf16 v[26:29], v[140:143], v[180:183], v[26:29]
	v_mfma_f32_16x16x32_bf16 v[14:17], v[132:135], v[188:191], v[14:17]
	v_mfma_f32_16x16x32_bf16 v[10:13], v[140:143], v[188:191], v[10:13]
	v_mfma_f32_16x16x32_bf16 v[62:65], v[136:139], v[168:171], v[62:65]
	v_mfma_f32_16x16x32_bf16 v[58:61], v[144:147], v[168:171], v[58:61]
	v_mfma_f32_16x16x32_bf16 v[46:49], v[136:139], v[176:179], v[46:49]
	v_mfma_f32_16x16x32_bf16 v[42:45], v[144:147], v[176:179], v[42:45]
	v_mfma_f32_16x16x32_bf16 v[30:33], v[136:139], v[184:187], v[30:33]
	v_mfma_f32_16x16x32_bf16 v[26:29], v[144:147], v[184:187], v[26:29]
	v_mfma_f32_16x16x32_bf16 v[14:17], v[136:139], v[192:195], v[14:17]
	v_mfma_f32_16x16x32_bf16 v[10:13], v[144:147], v[192:195], v[10:13]
	s_setprio 0
	s_setprio 1
	v_mfma_f32_16x16x32_bf16 v[54:57], v[148:151], v[164:167], v[54:57]
	v_mfma_f32_16x16x32_bf16 v[50:53], v[156:159], v[164:167], v[50:53]
	v_mfma_f32_16x16x32_bf16 v[38:41], v[148:151], v[172:175], v[38:41]
	v_mfma_f32_16x16x32_bf16 v[34:37], v[156:159], v[172:175], v[34:37]
	v_mfma_f32_16x16x32_bf16 v[22:25], v[148:151], v[180:183], v[22:25]
	v_mfma_f32_16x16x32_bf16 v[18:21], v[156:159], v[180:183], v[18:21]
	v_mfma_f32_16x16x32_bf16 v[6:9], v[148:151], v[188:191], v[6:9]
	v_mfma_f32_16x16x32_bf16 v[2:5], v[156:159], v[188:191], v[2:5]
	v_mfma_f32_16x16x32_bf16 v[54:57], v[152:155], v[168:171], v[54:57]
	v_mfma_f32_16x16x32_bf16 v[50:53], v[160:163], v[168:171], v[50:53]
	v_mfma_f32_16x16x32_bf16 v[38:41], v[152:155], v[176:179], v[38:41]
	v_mfma_f32_16x16x32_bf16 v[34:37], v[160:163], v[176:179], v[34:37]
	v_mfma_f32_16x16x32_bf16 v[22:25], v[152:155], v[184:187], v[22:25]
	v_mfma_f32_16x16x32_bf16 v[18:21], v[160:163], v[184:187], v[18:21]
	v_mfma_f32_16x16x32_bf16 v[6:9], v[152:155], v[192:195], v[6:9]
	v_mfma_f32_16x16x32_bf16 v[2:5], v[160:163], v[192:195], v[2:5]
	s_barrier
	s_setprio 0
	s_add_i32 s51, s51, 2
	s_add_u32 s24, s24, 0x100
	s_addc_u32 s31, s31, 0
	s_add_u32 s16, s16, 0x100
	s_addc_u32 s17, s17, 0
	s_cmp_gt_u32 s51, 5
	s_cbranch_scc0 .LBB0_444
	s_and_b64 vcc, exec, s[10:11]
	s_cbranch_vccz .LBB0_447
	s_barrier

; #define PG8_STAGE(bufoff, gbase, voff) do { _Pragma("unroll") for (int _i = 0; _i < 2; ++_i) \
;         __builtin_amdgcn_global_load_lds((const gunsigned*)((const gchar*)(gbase) + (voff)[_i]), (LAS unsigned*)(lds + (bufoff) + ldsw + _i * 8192), 16, 0, 0); } while (0)
; #define PG8_LDA(dst, b, h) do { _Pragma("unroll") for (int m = 0; m < 4; ++m) _Pragma("unroll") for (int k = 0; k < 2; ++k) dst[m][k] = *(const LAS bf16x8*)(lds + PG8_SA(b, h) + aoff + m * 2048 + k * 1024); } while (0)
; #define PG8_LDB(dst, b, h) do { _Pragma("unroll") for (int n = 0; n < 2; ++n) _Pragma("unroll") for (int k = 0; k < 2; ++k) dst[n][k] = *(const LAS bf16x8*)(lds + PG8_SB(b, h) + boff + n * 2048 + k * 1024); } while (0)
; #define PG8_MMA(ai, bj, At, Bt) do { __builtin_amdgcn_s_setprio(1); _Pragma("unroll") for (int m = 0; m < 4; ++m) _Pragma("unroll") for (int n = 0; n < 2; ++n) _Pragma("unroll") for (int k = 0; k < 2; ++k) \
;         acc[ai][bj][m][n] = __builtin_amdgcn_mfma_f32_16x16x32_bf16(Bt[n][k], At[m][k], acc[ai][bj][m][n], 0, 0, 0); __builtin_amdgcn_s_setprio(0); } while (0)
; #define PG8_WAIT_V(n) asm volatile("s_waitcnt vmcnt(" #n ")" ::: "memory")
; #define PG8_WAIT_L(n) asm volatile("s_waitcnt lgkmcnt(" #n ")" ::: "memory")
; #define PG8_BAR __builtin_amdgcn_s_barrier()
; #define PG8_SCHED __builtin_amdgcn_sched_barrier(0)
; template <class Epi, class Sched>
; __device__ __forceinline__ void gemm_phase(LAS unsigned char* lds, const int tid, const Gemm g, const Sched& S, const Epi& E) {
;     ...
;         for (int t = 0; t < nt; t += 2) {
;             const bool last = (t == nt - 2);
;             const gchar* a1 = cA + (size_t)(t + 1) * kstep;
;             const gchar* a2 = last ? nA : cA + (size_t)(t + 2) * kstep; const gchar* b2 = last ? nB : cB + (size_t)(t + 2) * kstep;
;             const gchar* a3 = a2 + kstep; const gchar* b3 = b2 + kstep;
;             PG8_LDB(B0, 0, 0); PG8_LDB(B1, 0, 1); PG8_SCHED; PG8_LDA(At, 0, 0); PG8_STAGE(PG8_SA(1, 1), a1 + hstep, voffA);
;             PG8_WAIT_V(8); PG8_WAIT_L(0); PG8_BAR; PG8_MMA(0, 0, At, B0); PG8_MMA(0, 1, At, B1); PG8_BAR; PG8_SCHED;
;             PG8_LDA(At, 0, 1); PG8_STAGE(PG8_SB(0, 0), b2, voffB); PG8_STAGE(PG8_SB(0, 1), b2 + hstep, voffB); PG8_STAGE(PG8_SA(0, 0), a2, voffA);
;             PG8_WAIT_V(8); PG8_WAIT_L(0); PG8_BAR; PG8_MMA(1, 0, At, B0); PG8_MMA(1, 1, At, B1); PG8_BAR; PG8_SCHED;
.LBB0_559:
	s_add_u32 s20, s60, 0xfffc0080
	s_addc_u32 s21, s61, -1
	s_add_i32 s29, 0, 0x10000
	s_cmp_eq_u32 s46, 12
	s_cselect_b32 s63, s9, s21
	s_cselect_b32 s62, s42, s20
	s_cselect_b32 s21, s7, s45
	s_cselect_b32 s20, s43, s44
	s_add_i32 s30, 0, 0x14000
	v_add_u32_e32 v152, s29, v165
	v_add_u32_e32 v160, s30, v165
	ds_read_b128 v[130:133], v152
	ds_read_b128 v[144:147], v152 offset:1024
	ds_read_b128 v[148:151], v152 offset:2048
	ds_read_b128 v[152:155], v152 offset:3072
	ds_read_b128 v[156:159], v160
	ds_read_b128 v[170:173], v160 offset:1024
	ds_read_b128 v[174:177], v160 offset:2048
	ds_read_b128 v[178:181], v160 offset:3072
	s_add_i32 m0, s34, 0xc000
	ds_read_b128 v[182:185], v169
	ds_read_b128 v[186:189], v169 offset:1024
	ds_read_b128 v[190:193], v169 offset:2048
	ds_read_b128 v[204:207], v169 offset:3072
	ds_read_b128 v[210:213], v169 offset:4096
	ds_read_b128 v[214:217], v169 offset:5120
	ds_read_b128 v[218:221], v169 offset:6144
	ds_read_b128 v[222:225], v169 offset:7168
	global_load_lds_dwordx4 v142, s[60:61]
	s_add_i32 m0, s34, 0xe000
	s_nop 0
	global_load_lds_dwordx4 v140, s[60:61]
	s_waitcnt vmcnt(8) lgkmcnt(0)
	s_setprio 1
	s_barrier
	v_mfma_f32_16x16x32_bf16 v[126:129], v[130:133], v[182:185], v[126:129]
	v_mfma_f32_16x16x32_bf16 v[122:125], v[148:151], v[182:185], v[122:125]
	v_mfma_f32_16x16x32_bf16 v[118:121], v[130:133], v[190:193], v[118:121]
	v_mfma_f32_16x16x32_bf16 v[110:113], v[148:151], v[190:193], v[110:113]
	v_mfma_f32_16x16x32_bf16 v[102:105], v[130:133], v[210:213], v[102:105]
	v_mfma_f32_16x16x32_bf16 v[94:97], v[148:151], v[210:213], v[94:97]
	v_mfma_f32_16x16x32_bf16 v[86:89], v[130:133], v[218:221], v[86:89]
	v_mfma_f32_16x16x32_bf16 v[78:81], v[148:151], v[218:221], v[78:81]
	v_mfma_f32_16x16x32_bf16 v[126:129], v[144:147], v[186:189], v[126:129]
	v_mfma_f32_16x16x32_bf16 v[122:125], v[152:155], v[186:189], v[122:125]
	v_mfma_f32_16x16x32_bf16 v[118:121], v[144:147], v[204:207], v[118:121]
	v_mfma_f32_16x16x32_bf16 v[110:113], v[152:155], v[204:207], v[110:113]
	v_mfma_f32_16x16x32_bf16 v[102:105], v[144:147], v[214:217], v[102:105]
	v_mfma_f32_16x16x32_bf16 v[94:97], v[152:155], v[214:217], v[94:97]
	v_mfma_f32_16x16x32_bf16 v[86:89], v[144:147], v[222:225], v[86:89]
	v_mfma_f32_16x16x32_bf16 v[78:81], v[152:155], v[222:225], v[78:81]
	s_setprio 0
	s_setprio 1
	v_mfma_f32_16x16x32_bf16 v[114:117], v[156:159], v[182:185], v[114:117]
	v_mfma_f32_16x16x32_bf16 v[106:109], v[174:177], v[182:185], v[106:109]
	v_mfma_f32_16x16x32_bf16 v[98:101], v[156:159], v[190:193], v[98:101]
	v_mfma_f32_16x16x32_bf16 v[90:93], v[174:177], v[190:193], v[90:93]
	v_mfma_f32_16x16x32_bf16 v[82:85], v[156:159], v[210:213], v[82:85]
	v_mfma_f32_16x16x32_bf16 v[74:77], v[174:177], v[210:213], v[74:77]
	v_mfma_f32_16x16x32_bf16 v[70:73], v[156:159], v[218:221], v[70:73]
	v_mfma_f32_16x16x32_bf16 v[66:69], v[174:177], v[218:221], v[66:69]
	v_mfma_f32_16x16x32_bf16 v[114:117], v[170:173], v[186:189], v[114:117]
	v_mfma_f32_16x16x32_bf16 v[106:109], v[178:181], v[186:189], v[106:109]
	v_mfma_f32_16x16x32_bf16 v[98:101], v[170:173], v[204:207], v[98:101]
	v_mfma_f32_16x16x32_bf16 v[90:93], v[178:181], v[204:207], v[90:93]
	v_mfma_f32_16x16x32_bf16 v[82:85], v[170:173], v[214:217], v[82:85]
	v_mfma_f32_16x16x32_bf16 v[74:77], v[178:181], v[214:217], v[74:77]
	v_mfma_f32_16x16x32_bf16 v[70:73], v[170:173], v[222:225], v[70:73]
	v_mfma_f32_16x16x32_bf16 v[66:69], v[178:181], v[222:225], v[66:69]
	s_barrier
	s_setprio 0
	s_add_i32 s29, s29, s12
	s_mov_b32 m0, s29
	ds_read_b128 v[182:185], v169 offset:16384
	ds_read_b128 v[186:189], v169 offset:17408
	ds_read_b128 v[190:193], v169 offset:18432
	ds_read_b128 v[204:207], v169 offset:19456
	ds_read_b128 v[210:213], v169 offset:20480
	ds_read_b128 v[214:217], v169 offset:21504
	ds_read_b128 v[218:221], v169 offset:22528
	ds_read_b128 v[222:225], v169 offset:23552
	global_load_lds_dwordx4 v0, s[20:21]
	s_add_i32 m0, s29, 0x2000
	s_add_u32 s48, s20, 0x40000
	s_addc_u32 s49, s21, 0
	s_add_i32 s29, s30, s12
	global_load_lds_dwordx4 v134, s[20:21]
	s_mov_b32 m0, s29
	s_nop 0
	global_load_lds_dwordx4 v0, s[48:49]
	s_add_i32 m0, s29, 0x2000
	s_nop 0
	global_load_lds_dwordx4 v134, s[48:49]
	s_mov_b32 m0, s34
	s_nop 0
	global_load_lds_dwordx4 v138, s[62:63]
	s_mov_b32 m0, s35
	s_nop 0
	global_load_lds_dwordx4 v136, s[62:63]
	s_waitcnt vmcnt(8) lgkmcnt(0)
	s_setprio 1
	s_barrier
	v_mfma_f32_16x16x32_bf16 v[62:65], v[130:133], v[182:185], v[62:65]
	v_mfma_f32_16x16x32_bf16 v[58:61], v[148:151], v[182:185], v[58:61]
	v_mfma_f32_16x16x32_bf16 v[54:57], v[130:133], v[190:193], v[54:57]
	v_mfma_f32_16x16x32_bf16 v[46:49], v[148:151], v[190:193], v[46:49]
	v_mfma_f32_16x16x32_bf16 v[38:41], v[130:133], v[210:213], v[38:41]
	v_mfma_f32_16x16x32_bf16 v[30:33], v[148:151], v[210:213], v[30:33]
	v_mfma_f32_16x16x32_bf16 v[22:25], v[130:133], v[218:221], v[22:25]
	v_mfma_f32_16x16x32_bf16 v[14:17], v[148:151], v[218:221], v[14:17]
	v_mfma_f32_16x16x32_bf16 v[62:65], v[144:147], v[186:189], v[62:65]
	v_mfma_f32_16x16x32_bf16 v[58:61], v[152:155], v[186:189], v[58:61]
	v_mfma_f32_16x16x32_bf16 v[54:57], v[144:147], v[204:207], v[54:57]
	v_mfma_f32_16x16x32_bf16 v[46:49], v[152:155], v[204:207], v[46:49]
	v_mfma_f32_16x16x32_bf16 v[38:41], v[144:147], v[214:217], v[38:41]
	v_mfma_f32_16x16x32_bf16 v[30:33], v[152:155], v[214:217], v[30:33]
	v_mfma_f32_16x16x32_bf16 v[22:25], v[144:147], v[222:225], v[22:25]
	v_mfma_f32_16x16x32_bf16 v[14:17], v[152:155], v[222:225], v[14:17]
	s_setprio 0
	s_setprio 1
	v_mfma_f32_16x16x32_bf16 v[50:53], v[156:159], v[182:185], v[50:53]
	v_mfma_f32_16x16x32_bf16 v[42:45], v[174:177], v[182:185], v[42:45]
	v_mfma_f32_16x16x32_bf16 v[34:37], v[156:159], v[190:193], v[34:37]
	v_mfma_f32_16x16x32_bf16 v[26:29], v[174:177], v[190:193], v[26:29]
	v_mfma_f32_16x16x32_bf16 v[18:21], v[156:159], v[210:213], v[18:21]
	v_mfma_f32_16x16x32_bf16 v[10:13], v[174:177], v[210:213], v[10:13]
	v_mfma_f32_16x16x32_bf16 v[6:9], v[156:159], v[218:221], v[6:9]
	v_mfma_f32_16x16x32_bf16 v[2:5], v[174:177], v[218:221], v[2:5]
	v_mfma_f32_16x16x32_bf16 v[50:53], v[170:173], v[186:189], v[50:53]
	v_mfma_f32_16x16x32_bf16 v[42:45], v[178:181], v[186:189], v[42:45]
	v_mfma_f32_16x16x32_bf16 v[34:37], v[170:173], v[204:207], v[34:37]
	v_mfma_f32_16x16x32_bf16 v[26:29], v[178:181], v[204:207], v[26:29]
	v_mfma_f32_16x16x32_bf16 v[18:21], v[170:173], v[214:217], v[18:21]
	v_mfma_f32_16x16x32_bf16 v[10:13], v[178:181], v[214:217], v[10:13]
	v_mfma_f32_16x16x32_bf16 v[6:9], v[170:173], v[222:225], v[6:9]
	v_mfma_f32_16x16x32_bf16 v[2:5], v[178:181], v[222:225], v[2:5]
	s_barrier
; #define PG8_STAGE(bufoff, gbase, voff) do { _Pragma("unroll") for (int _i = 0; _i < 2; ++_i) \
;         __builtin_amdgcn_global_load_lds((const gunsigned*)((const gchar*)(gbase) + (voff)[_i]), (LAS unsigned*)(lds + (bufoff) + ldsw + _i * 8192), 16, 0, 0); } while (0)
; #define PG8_LDA(dst, b, h) do { _Pragma("unroll") for (int m = 0; m < 4; ++m) _Pragma("unroll") for (int k = 0; k < 2; ++k) dst[m][k] = *(const LAS bf16x8*)(lds + PG8_SA(b, h) + aoff + m * 2048 + k * 1024); } while (0)
; #define PG8_LDB(dst, b, h) do { _Pragma("unroll") for (int n = 0; n < 2; ++n) _Pragma("unroll") for (int k = 0; k < 2; ++k) dst[n][k] = *(const LAS bf16x8*)(lds + PG8_SB(b, h) + boff + n * 2048 + k * 1024); } while (0)
; #define PG8_MMA(ai, bj, At, Bt) do { __builtin_amdgcn_s_setprio(1); _Pragma("unroll") for (int m = 0; m < 4; ++m) _Pragma("unroll") for (int n = 0; n < 2; ++n) _Pragma("unroll") for (int k = 0; k < 2; ++k) \
;         acc[ai][bj][m][n] = __builtin_amdgcn_mfma_f32_16x16x32_bf16(Bt[n][k], At[m][k], acc[ai][bj][m][n], 0, 0, 0); __builtin_amdgcn_s_setprio(0); } while (0)
; #define PG8_WAIT_V(n) asm volatile("s_waitcnt vmcnt(" #n ")" ::: "memory")
; #define PG8_WAIT_L(n) asm volatile("s_waitcnt lgkmcnt(" #n ")" ::: "memory")
; #define PG8_BAR __builtin_amdgcn_s_barrier()
; #define PG8_SCHED __builtin_amdgcn_sched_barrier(0)
; template <class Epi, class Sched>
; __device__ __forceinline__ void gemm_phase(LAS unsigned char* lds, const int tid, const Gemm g, const Sched& S, const Epi& E) {
;     ...
;             PG8_LDB(B0, 1, 0); PG8_LDB(B1, 1, 1); PG8_SCHED; PG8_LDA(At, 1, 0); PG8_STAGE(PG8_SA(0, 1), a2 + hstep, voffA);
;             PG8_WAIT_V(8); PG8_WAIT_L(0); PG8_BAR; PG8_MMA(0, 0, At, B0); PG8_MMA(0, 1, At, B1); PG8_BAR; PG8_SCHED;
;             PG8_LDA(At, 1, 1); PG8_STAGE(PG8_SB(1, 0), b3, voffB); PG8_STAGE(PG8_SB(1, 1), b3 + hstep, voffB); PG8_STAGE(PG8_SA(1, 0), a3, voffA);
;             PG8_WAIT_V(8); PG8_WAIT_L(0); PG8_BAR; PG8_MMA(1, 0, At, B0); PG8_MMA(1, 1, At, B1); PG8_BAR; PG8_SCHED;
;         }
;         if (wr == 0) PG8_BAR;
	s_setprio 0
	s_add_i32 s29, 0, 0x18000
	s_add_i32 s30, 0, 0x1c000
	v_add_u32_e32 v152, s29, v165
	v_add_u32_e32 v162, s30, v165
	ds_read_b128 v[130:133], v152
	ds_read_b128 v[144:147], v152 offset:1024
	ds_read_b128 v[148:151], v152 offset:2048
	ds_read_b128 v[152:155], v152 offset:3072
	ds_read_b128 v[156:159], v162
	ds_read_b128 v[170:173], v162 offset:1024
	ds_read_b128 v[174:177], v162 offset:2048
	ds_read_b128 v[178:181], v162 offset:3072
	s_add_u32 s48, s62, 0x40000
	s_addc_u32 s49, s63, 0
	s_mov_b32 m0, s36
	ds_read_b128 v[182:185], v169 offset:32768
	ds_read_b128 v[186:189], v169 offset:33792
	ds_read_b128 v[190:193], v169 offset:34816
	ds_read_b128 v[204:207], v169 offset:35840
	ds_read_b128 v[210:213], v169 offset:36864
	ds_read_b128 v[214:217], v169 offset:37888
	ds_read_b128 v[218:221], v169 offset:38912
	ds_read_b128 v[222:225], v169 offset:39936
	global_load_lds_dwordx4 v138, s[48:49]
	s_mov_b32 m0, s37
	s_nop 0
	global_load_lds_dwordx4 v136, s[48:49]
	s_waitcnt vmcnt(8) lgkmcnt(0)
	s_setprio 1
	s_barrier
	v_mfma_f32_16x16x32_bf16 v[126:129], v[130:133], v[182:185], v[126:129]
	v_mfma_f32_16x16x32_bf16 v[122:125], v[148:151], v[182:185], v[122:125]
	v_mfma_f32_16x16x32_bf16 v[118:121], v[130:133], v[190:193], v[118:121]
	v_mfma_f32_16x16x32_bf16 v[110:113], v[148:151], v[190:193], v[110:113]
	v_mfma_f32_16x16x32_bf16 v[102:105], v[130:133], v[210:213], v[102:105]
	v_mfma_f32_16x16x32_bf16 v[94:97], v[148:151], v[210:213], v[94:97]
	v_mfma_f32_16x16x32_bf16 v[86:89], v[130:133], v[218:221], v[86:89]
	v_mfma_f32_16x16x32_bf16 v[78:81], v[148:151], v[218:221], v[78:81]
	v_mfma_f32_16x16x32_bf16 v[126:129], v[144:147], v[186:189], v[126:129]
	v_mfma_f32_16x16x32_bf16 v[122:125], v[152:155], v[186:189], v[122:125]
	v_mfma_f32_16x16x32_bf16 v[118:121], v[144:147], v[204:207], v[118:121]
	v_mfma_f32_16x16x32_bf16 v[110:113], v[152:155], v[204:207], v[110:113]
	v_mfma_f32_16x16x32_bf16 v[102:105], v[144:147], v[214:217], v[102:105]
	v_mfma_f32_16x16x32_bf16 v[94:97], v[152:155], v[214:217], v[94:97]
	v_mfma_f32_16x16x32_bf16 v[86:89], v[144:147], v[222:225], v[86:89]
	v_mfma_f32_16x16x32_bf16 v[78:81], v[152:155], v[222:225], v[78:81]
	s_setprio 0
	s_setprio 1
	v_mfma_f32_16x16x32_bf16 v[114:117], v[156:159], v[182:185], v[114:117]
	v_mfma_f32_16x16x32_bf16 v[106:109], v[174:177], v[182:185], v[106:109]
	v_mfma_f32_16x16x32_bf16 v[98:101], v[156:159], v[190:193], v[98:101]
	v_mfma_f32_16x16x32_bf16 v[90:93], v[174:177], v[190:193], v[90:93]
	v_mfma_f32_16x16x32_bf16 v[82:85], v[156:159], v[210:213], v[82:85]
	v_mfma_f32_16x16x32_bf16 v[74:77], v[174:177], v[210:213], v[74:77]
	v_mfma_f32_16x16x32_bf16 v[70:73], v[156:159], v[218:221], v[70:73]
	v_mfma_f32_16x16x32_bf16 v[66:69], v[174:177], v[218:221], v[66:69]
	v_mfma_f32_16x16x32_bf16 v[114:117], v[170:173], v[186:189], v[114:117]
	v_mfma_f32_16x16x32_bf16 v[106:109], v[178:181], v[186:189], v[106:109]
	v_mfma_f32_16x16x32_bf16 v[98:101], v[170:173], v[204:207], v[98:101]
	v_mfma_f32_16x16x32_bf16 v[90:93], v[178:181], v[204:207], v[90:93]
	v_mfma_f32_16x16x32_bf16 v[82:85], v[170:173], v[214:217], v[82:85]
	v_mfma_f32_16x16x32_bf16 v[74:77], v[178:181], v[214:217], v[74:77]
	v_mfma_f32_16x16x32_bf16 v[70:73], v[170:173], v[222:225], v[70:73]
	v_mfma_f32_16x16x32_bf16 v[66:69], v[178:181], v[222:225], v[66:69]
	s_barrier
	s_setprio 0
	s_add_i32 s29, s29, s12
	s_mov_b32 m0, s29
	ds_read_b128 v[182:185], v169 offset:49152
	ds_read_b128 v[186:189], v169 offset:50176
	ds_read_b128 v[190:193], v169 offset:51200
	ds_read_b128 v[204:207], v169 offset:52224
	ds_read_b128 v[210:213], v169 offset:53248
	ds_read_b128 v[214:217], v169 offset:54272
	ds_read_b128 v[218:221], v169 offset:55296
	ds_read_b128 v[222:225], v169 offset:56320
	global_load_lds_dwordx4 v161, s[20:21]
	s_add_i32 m0, s29, 0x2000
	s_add_i32 s29, s30, s12
	global_load_lds_dwordx4 v195, s[20:21]
	s_add_u32 s20, s20, 0x40080
	s_addc_u32 s21, s21, 0
	s_mov_b32 m0, s29
	s_nop 0
	global_load_lds_dwordx4 v0, s[20:21]
	s_add_i32 m0, s29, 0x2000
	s_nop 0
	global_load_lds_dwordx4 v134, s[20:21]
	s_mov_b32 m0, s38
	s_nop 0
	global_load_lds_dwordx4 v201, s[62:63]
	s_mov_b32 m0, s39
	s_nop 0
	global_load_lds_dwordx4 v227, s[62:63]
	s_waitcnt vmcnt(8) lgkmcnt(0)
	s_setprio 1
	s_barrier
	v_mfma_f32_16x16x32_bf16 v[62:65], v[130:133], v[182:185], v[62:65]
	v_mfma_f32_16x16x32_bf16 v[58:61], v[148:151], v[182:185], v[58:61]
	v_mfma_f32_16x16x32_bf16 v[54:57], v[130:133], v[190:193], v[54:57]
	v_mfma_f32_16x16x32_bf16 v[46:49], v[148:151], v[190:193], v[46:49]
	v_mfma_f32_16x16x32_bf16 v[38:41], v[130:133], v[210:213], v[38:41]
	v_mfma_f32_16x16x32_bf16 v[30:33], v[148:151], v[210:213], v[30:33]
	v_mfma_f32_16x16x32_bf16 v[22:25], v[130:133], v[218:221], v[22:25]
	v_mfma_f32_16x16x32_bf16 v[14:17], v[148:151], v[218:221], v[14:17]
	v_mfma_f32_16x16x32_bf16 v[62:65], v[144:147], v[186:189], v[62:65]
	v_mfma_f32_16x16x32_bf16 v[58:61], v[152:155], v[186:189], v[58:61]
	v_mfma_f32_16x16x32_bf16 v[54:57], v[144:147], v[204:207], v[54:57]
	v_mfma_f32_16x16x32_bf16 v[46:49], v[152:155], v[204:207], v[46:49]
	v_mfma_f32_16x16x32_bf16 v[38:41], v[144:147], v[214:217], v[38:41]
	v_mfma_f32_16x16x32_bf16 v[30:33], v[152:155], v[214:217], v[30:33]
	v_mfma_f32_16x16x32_bf16 v[22:25], v[144:147], v[222:225], v[22:25]
	v_mfma_f32_16x16x32_bf16 v[14:17], v[152:155], v[222:225], v[14:17]
	s_setprio 0
	s_setprio 1
	v_mfma_f32_16x16x32_bf16 v[50:53], v[156:159], v[182:185], v[50:53]
	v_mfma_f32_16x16x32_bf16 v[42:45], v[174:177], v[182:185], v[42:45]
	v_mfma_f32_16x16x32_bf16 v[34:37], v[156:159], v[190:193], v[34:37]
	v_mfma_f32_16x16x32_bf16 v[26:29], v[174:177], v[190:193], v[26:29]
	v_mfma_f32_16x16x32_bf16 v[18:21], v[156:159], v[210:213], v[18:21]
	v_mfma_f32_16x16x32_bf16 v[10:13], v[174:177], v[210:213], v[10:13]
	v_mfma_f32_16x16x32_bf16 v[6:9], v[156:159], v[218:221], v[6:9]
	v_mfma_f32_16x16x32_bf16 v[2:5], v[174:177], v[218:221], v[2:5]
	v_mfma_f32_16x16x32_bf16 v[50:53], v[170:173], v[186:189], v[50:53]
	v_mfma_f32_16x16x32_bf16 v[42:45], v[178:181], v[186:189], v[42:45]
	v_mfma_f32_16x16x32_bf16 v[34:37], v[170:173], v[204:207], v[34:37]
	v_mfma_f32_16x16x32_bf16 v[26:29], v[178:181], v[204:207], v[26:29]
	v_mfma_f32_16x16x32_bf16 v[18:21], v[170:173], v[214:217], v[18:21]
	v_mfma_f32_16x16x32_bf16 v[10:13], v[178:181], v[214:217], v[10:13]
	v_mfma_f32_16x16x32_bf16 v[6:9], v[170:173], v[222:225], v[6:9]
	v_mfma_f32_16x16x32_bf16 v[2:5], v[178:181], v[222:225], v[2:5]
	s_barrier
	s_setprio 0
	s_add_i32 s46, s46, 2
	s_add_u32 s44, s44, 0x100
	s_addc_u32 s45, s45, 0
	s_add_u32 s60, s60, 0x100
	s_addc_u32 s61, s61, 0
	s_cmp_gt_u32 s46, 13
	s_cbranch_scc0 .LBB0_559
	s_and_b64 vcc, exec, s[4:5]
	s_cbranch_vccz .LBB0_562
	s_barrier

; #define PG8_STAGE(bufoff, gbase, voff) do { _Pragma("unroll") for (int _i = 0; _i < 2; ++_i) \
;         __builtin_amdgcn_global_load_lds((const gunsigned*)((const gchar*)(gbase) + (voff)[_i]), (LAS unsigned*)(lds + (bufoff) + ldsw + _i * 8192), 16, 0, 0); } while (0)
; #define PG8_LDA(dst, b, h) do { _Pragma("unroll") for (int m = 0; m < 4; ++m) _Pragma("unroll") for (int k = 0; k < 2; ++k) dst[m][k] = *(const LAS bf16x8*)(lds + PG8_SA(b, h) + aoff + m * 2048 + k * 1024); } while (0)
; #define PG8_LDB(dst, b, h) do { _Pragma("unroll") for (int n = 0; n < 2; ++n) _Pragma("unroll") for (int k = 0; k < 2; ++k) dst[n][k] = *(const LAS bf16x8*)(lds + PG8_SB(b, h) + boff + n * 2048 + k * 1024); } while (0)
; #define PG8_MMA(ai, bj, At, Bt) do { __builtin_amdgcn_s_setprio(1); _Pragma("unroll") for (int m = 0; m < 4; ++m) _Pragma("unroll") for (int n = 0; n < 2; ++n) _Pragma("unroll") for (int k = 0; k < 2; ++k) \
;         acc[ai][bj][m][n] = __builtin_amdgcn_mfma_f32_16x16x32_bf16(Bt[n][k], At[m][k], acc[ai][bj][m][n], 0, 0, 0); __builtin_amdgcn_s_setprio(0); } while (0)
; #define PG8_WAIT_V(n) asm volatile("s_waitcnt vmcnt(" #n ")" ::: "memory")
; #define PG8_WAIT_L(n) asm volatile("s_waitcnt lgkmcnt(" #n ")" ::: "memory")
; #define PG8_BAR __builtin_amdgcn_s_barrier()
; #define PG8_SCHED __builtin_amdgcn_sched_barrier(0)
; template <class Epi, class Sched>
; __device__ __forceinline__ void gemm_phase(LAS unsigned char* lds, const int tid, const Gemm g, const Sched& S, const Epi& E) {
;     ...
;         for (int t = 0; t < nt; t += 2) {
;             const bool last = (t == nt - 2);
;             const gchar* a1 = cA + (size_t)(t + 1) * kstep;
;             const gchar* a2 = last ? nA : cA + (size_t)(t + 2) * kstep; const gchar* b2 = last ? nB : cB + (size_t)(t + 2) * kstep;
;             const gchar* a3 = a2 + kstep; const gchar* b3 = b2 + kstep;
;             PG8_LDB(B0, 0, 0); PG8_LDB(B1, 0, 1); PG8_SCHED; PG8_LDA(At, 0, 0); PG8_STAGE(PG8_SA(1, 1), a1 + hstep, voffA);
;             PG8_WAIT_V(8); PG8_WAIT_L(0); PG8_BAR; PG8_MMA(0, 0, At, B0); PG8_MMA(0, 1, At, B1); PG8_BAR; PG8_SCHED;
;             PG8_LDA(At, 0, 1); PG8_STAGE(PG8_SB(0, 0), b2, voffB); PG8_STAGE(PG8_SB(0, 1), b2 + hstep, voffB); PG8_STAGE(PG8_SA(0, 0), a2, voffA);
;             PG8_WAIT_V(8); PG8_WAIT_L(0); PG8_BAR; PG8_MMA(1, 0, At, B0); PG8_MMA(1, 1, At, B1); PG8_BAR; PG8_SCHED;
.LBB0_598:
	s_add_u32 s20, s62, 0x100
	s_addc_u32 s21, s63, 0
	s_add_i32 s29, 0, 0x10000
	s_cmp_eq_u32 s45, 40
	s_cselect_b32 s73, s9, s21
	s_cselect_b32 s72, s8, s20
	s_cselect_b32 s67, s61, s44
	s_cselect_b32 s66, s60, s31
	s_add_i32 s48, 0, 0x14000
	v_add_u32_e32 v142, s29, v210
	v_add_u32_e32 v158, s48, v210
	ds_read_b128 v[130:133], v142
	ds_read_b128 v[134:137], v142 offset:1024
	ds_read_b128 v[138:141], v142 offset:2048
	ds_read_b128 v[142:145], v142 offset:3072
	ds_read_b128 v[146:149], v158
	ds_read_b128 v[150:153], v158 offset:1024
	ds_read_b128 v[154:157], v158 offset:2048
	ds_read_b128 v[158:161], v158 offset:3072
	s_add_i32 m0, s34, 0xc000
	ds_read_b128 v[162:165], v214
	ds_read_b128 v[166:169], v214 offset:1024
	ds_read_b128 v[170:173], v214 offset:2048
	ds_read_b128 v[174:177], v214 offset:3072
	ds_read_b128 v[188:191], v214 offset:4096
	ds_read_b128 v[192:195], v214 offset:5120
	ds_read_b128 v[204:207], v214 offset:6144
	ds_read_b128 v[216:219], v214 offset:7168
	global_load_lds_dwordx4 v186, s[62:63]
	s_add_i32 m0, s34, 0xe000
	s_nop 0
	global_load_lds_dwordx4 v184, s[62:63]
	s_waitcnt vmcnt(8) lgkmcnt(0)
	s_setprio 1
	s_barrier
	v_mfma_f32_16x16x32_bf16 v[126:129], v[130:133], v[162:165], v[126:129]
	v_mfma_f32_16x16x32_bf16 v[122:125], v[138:141], v[162:165], v[122:125]
	v_mfma_f32_16x16x32_bf16 v[110:113], v[130:133], v[170:173], v[110:113]
	v_mfma_f32_16x16x32_bf16 v[106:109], v[138:141], v[170:173], v[106:109]
	v_mfma_f32_16x16x32_bf16 v[94:97], v[130:133], v[188:191], v[94:97]
	v_mfma_f32_16x16x32_bf16 v[90:93], v[138:141], v[188:191], v[90:93]
	v_mfma_f32_16x16x32_bf16 v[78:81], v[130:133], v[204:207], v[78:81]
	v_mfma_f32_16x16x32_bf16 v[74:77], v[138:141], v[204:207], v[74:77]
	v_mfma_f32_16x16x32_bf16 v[126:129], v[134:137], v[166:169], v[126:129]
	v_mfma_f32_16x16x32_bf16 v[122:125], v[142:145], v[166:169], v[122:125]
	v_mfma_f32_16x16x32_bf16 v[110:113], v[134:137], v[174:177], v[110:113]
	v_mfma_f32_16x16x32_bf16 v[106:109], v[142:145], v[174:177], v[106:109]
	v_mfma_f32_16x16x32_bf16 v[94:97], v[134:137], v[192:195], v[94:97]
	v_mfma_f32_16x16x32_bf16 v[90:93], v[142:145], v[192:195], v[90:93]
	v_mfma_f32_16x16x32_bf16 v[78:81], v[134:137], v[216:219], v[78:81]
	v_mfma_f32_16x16x32_bf16 v[74:77], v[142:145], v[216:219], v[74:77]
	s_setprio 0
	s_setprio 1
	v_mfma_f32_16x16x32_bf16 v[118:121], v[146:149], v[162:165], v[118:121]
	v_mfma_f32_16x16x32_bf16 v[114:117], v[154:157], v[162:165], v[114:117]
	v_mfma_f32_16x16x32_bf16 v[102:105], v[146:149], v[170:173], v[102:105]
	v_mfma_f32_16x16x32_bf16 v[98:101], v[154:157], v[170:173], v[98:101]
	v_mfma_f32_16x16x32_bf16 v[86:89], v[146:149], v[188:191], v[86:89]
	v_mfma_f32_16x16x32_bf16 v[82:85], v[154:157], v[188:191], v[82:85]
	v_mfma_f32_16x16x32_bf16 v[70:73], v[146:149], v[204:207], v[70:73]
	v_mfma_f32_16x16x32_bf16 v[66:69], v[154:157], v[204:207], v[66:69]
	v_mfma_f32_16x16x32_bf16 v[118:121], v[150:153], v[166:169], v[118:121]
	v_mfma_f32_16x16x32_bf16 v[114:117], v[158:161], v[166:169], v[114:117]
	v_mfma_f32_16x16x32_bf16 v[102:105], v[150:153], v[174:177], v[102:105]
	v_mfma_f32_16x16x32_bf16 v[98:101], v[158:161], v[174:177], v[98:101]
	v_mfma_f32_16x16x32_bf16 v[86:89], v[150:153], v[192:195], v[86:89]
	v_mfma_f32_16x16x32_bf16 v[82:85], v[158:161], v[192:195], v[82:85]
	v_mfma_f32_16x16x32_bf16 v[70:73], v[150:153], v[216:219], v[70:73]
	v_mfma_f32_16x16x32_bf16 v[66:69], v[158:161], v[216:219], v[66:69]
	s_barrier
	s_setprio 0
	s_add_i32 s29, s29, s15
	s_mov_b32 m0, s29
	ds_read_b128 v[162:165], v214 offset:16384
	ds_read_b128 v[166:169], v214 offset:17408
	ds_read_b128 v[170:173], v214 offset:18432
	ds_read_b128 v[174:177], v214 offset:19456
	ds_read_b128 v[188:191], v214 offset:20480
	ds_read_b128 v[192:195], v214 offset:21504
	ds_read_b128 v[204:207], v214 offset:22528
	ds_read_b128 v[216:219], v214 offset:23552
	global_load_lds_dwordx4 v0, s[66:67]
	s_add_i32 m0, s29, 0x2000
	s_add_u32 s46, s66, 0xb0000
	s_addc_u32 s47, s67, 0
	s_add_i32 s29, s48, s15
	global_load_lds_dwordx4 v182, s[66:67]
	s_mov_b32 m0, s29
	s_nop 0
	global_load_lds_dwordx4 v0, s[46:47]
	s_add_i32 m0, s29, 0x2000
	s_nop 0
	global_load_lds_dwordx4 v182, s[46:47]
	s_mov_b32 m0, s34
	s_nop 0
	global_load_lds_dwordx4 v178, s[72:73]
	s_mov_b32 m0, s12
	s_nop 0
	global_load_lds_dwordx4 v180, s[72:73]
	s_waitcnt vmcnt(8) lgkmcnt(0)
	s_setprio 1
	s_barrier
	v_mfma_f32_16x16x32_bf16 v[62:65], v[130:133], v[162:165], v[62:65]
	v_mfma_f32_16x16x32_bf16 v[58:61], v[138:141], v[162:165], v[58:61]
	v_mfma_f32_16x16x32_bf16 v[46:49], v[130:133], v[170:173], v[46:49]
	v_mfma_f32_16x16x32_bf16 v[42:45], v[138:141], v[170:173], v[42:45]
	v_mfma_f32_16x16x32_bf16 v[30:33], v[130:133], v[188:191], v[30:33]
	v_mfma_f32_16x16x32_bf16 v[26:29], v[138:141], v[188:191], v[26:29]
	v_mfma_f32_16x16x32_bf16 v[14:17], v[130:133], v[204:207], v[14:17]
	v_mfma_f32_16x16x32_bf16 v[10:13], v[138:141], v[204:207], v[10:13]
	v_mfma_f32_16x16x32_bf16 v[62:65], v[134:137], v[166:169], v[62:65]
	v_mfma_f32_16x16x32_bf16 v[58:61], v[142:145], v[166:169], v[58:61]
	v_mfma_f32_16x16x32_bf16 v[46:49], v[134:137], v[174:177], v[46:49]
	v_mfma_f32_16x16x32_bf16 v[42:45], v[142:145], v[174:177], v[42:45]
	v_mfma_f32_16x16x32_bf16 v[30:33], v[134:137], v[192:195], v[30:33]
	v_mfma_f32_16x16x32_bf16 v[26:29], v[142:145], v[192:195], v[26:29]
	v_mfma_f32_16x16x32_bf16 v[14:17], v[134:137], v[216:219], v[14:17]
	v_mfma_f32_16x16x32_bf16 v[10:13], v[142:145], v[216:219], v[10:13]
	s_setprio 0
	s_setprio 1
	v_mfma_f32_16x16x32_bf16 v[54:57], v[146:149], v[162:165], v[54:57]
	v_mfma_f32_16x16x32_bf16 v[50:53], v[154:157], v[162:165], v[50:53]
	v_mfma_f32_16x16x32_bf16 v[38:41], v[146:149], v[170:173], v[38:41]
	v_mfma_f32_16x16x32_bf16 v[34:37], v[154:157], v[170:173], v[34:37]
	v_mfma_f32_16x16x32_bf16 v[22:25], v[146:149], v[188:191], v[22:25]
	v_mfma_f32_16x16x32_bf16 v[18:21], v[154:157], v[188:191], v[18:21]
	v_mfma_f32_16x16x32_bf16 v[6:9], v[146:149], v[204:207], v[6:9]
	v_mfma_f32_16x16x32_bf16 v[2:5], v[154:157], v[204:207], v[2:5]
	v_mfma_f32_16x16x32_bf16 v[54:57], v[150:153], v[166:169], v[54:57]
	v_mfma_f32_16x16x32_bf16 v[50:53], v[158:161], v[166:169], v[50:53]
	v_mfma_f32_16x16x32_bf16 v[38:41], v[150:153], v[174:177], v[38:41]
	v_mfma_f32_16x16x32_bf16 v[34:37], v[158:161], v[174:177], v[34:37]
	v_mfma_f32_16x16x32_bf16 v[22:25], v[150:153], v[192:195], v[22:25]
	v_mfma_f32_16x16x32_bf16 v[18:21], v[158:161], v[192:195], v[18:21]
	v_mfma_f32_16x16x32_bf16 v[6:9], v[150:153], v[216:219], v[6:9]
	v_mfma_f32_16x16x32_bf16 v[2:5], v[158:161], v[216:219], v[2:5]
	s_barrier
; #define PG8_STAGE(bufoff, gbase, voff) do { _Pragma("unroll") for (int _i = 0; _i < 2; ++_i) \
;         __builtin_amdgcn_global_load_lds((const gunsigned*)((const gchar*)(gbase) + (voff)[_i]), (LAS unsigned*)(lds + (bufoff) + ldsw + _i * 8192), 16, 0, 0); } while (0)
; #define PG8_LDA(dst, b, h) do { _Pragma("unroll") for (int m = 0; m < 4; ++m) _Pragma("unroll") for (int k = 0; k < 2; ++k) dst[m][k] = *(const LAS bf16x8*)(lds + PG8_SA(b, h) + aoff + m * 2048 + k * 1024); } while (0)
; #define PG8_LDB(dst, b, h) do { _Pragma("unroll") for (int n = 0; n < 2; ++n) _Pragma("unroll") for (int k = 0; k < 2; ++k) dst[n][k] = *(const LAS bf16x8*)(lds + PG8_SB(b, h) + boff + n * 2048 + k * 1024); } while (0)
; #define PG8_MMA(ai, bj, At, Bt) do { __builtin_amdgcn_s_setprio(1); _Pragma("unroll") for (int m = 0; m < 4; ++m) _Pragma("unroll") for (int n = 0; n < 2; ++n) _Pragma("unroll") for (int k = 0; k < 2; ++k) \
;         acc[ai][bj][m][n] = __builtin_amdgcn_mfma_f32_16x16x32_bf16(Bt[n][k], At[m][k], acc[ai][bj][m][n], 0, 0, 0); __builtin_amdgcn_s_setprio(0); } while (0)
; #define PG8_WAIT_V(n) asm volatile("s_waitcnt vmcnt(" #n ")" ::: "memory")
; #define PG8_WAIT_L(n) asm volatile("s_waitcnt lgkmcnt(" #n ")" ::: "memory")
; #define PG8_BAR __builtin_amdgcn_s_barrier()
; #define PG8_SCHED __builtin_amdgcn_sched_barrier(0)
; template <class Epi, class Sched>
; __device__ __forceinline__ void gemm_phase(LAS unsigned char* lds, const int tid, const Gemm g, const Sched& S, const Epi& E) {
;     ...
;             PG8_LDB(B0, 1, 0); PG8_LDB(B1, 1, 1); PG8_SCHED; PG8_LDA(At, 1, 0); PG8_STAGE(PG8_SA(0, 1), a2 + hstep, voffA);
;             PG8_WAIT_V(8); PG8_WAIT_L(0); PG8_BAR; PG8_MMA(0, 0, At, B0); PG8_MMA(0, 1, At, B1); PG8_BAR; PG8_SCHED;
;             PG8_LDA(At, 1, 1); PG8_STAGE(PG8_SB(1, 0), b3, voffB); PG8_STAGE(PG8_SB(1, 1), b3 + hstep, voffB); PG8_STAGE(PG8_SA(1, 0), a3, voffA);
;             PG8_WAIT_V(8); PG8_WAIT_L(0); PG8_BAR; PG8_MMA(1, 0, At, B0); PG8_MMA(1, 1, At, B1); PG8_BAR; PG8_SCHED;
;         }
;         if (wr == 0) PG8_BAR;
	s_setprio 0
	s_add_i32 s29, 0, 0x18000
	s_add_i32 s48, 0, 0x1c000
	v_add_u32_e32 v142, s29, v210
	v_add_u32_e32 v158, s48, v210
	ds_read_b128 v[130:133], v142
	ds_read_b128 v[134:137], v142 offset:1024
	ds_read_b128 v[138:141], v142 offset:2048
	ds_read_b128 v[142:145], v142 offset:3072
	ds_read_b128 v[146:149], v158
	ds_read_b128 v[150:153], v158 offset:1024
	ds_read_b128 v[154:157], v158 offset:2048
	ds_read_b128 v[158:161], v158 offset:3072
	s_add_u32 s46, s72, 0xb0000
	s_addc_u32 s47, s73, 0
	s_mov_b32 m0, s35
	ds_read_b128 v[162:165], v214 offset:32768
	ds_read_b128 v[166:169], v214 offset:33792
	ds_read_b128 v[170:173], v214 offset:34816
	ds_read_b128 v[174:177], v214 offset:35840
	ds_read_b128 v[188:191], v214 offset:36864
	ds_read_b128 v[192:195], v214 offset:37888
	ds_read_b128 v[204:207], v214 offset:38912
	ds_read_b128 v[216:219], v214 offset:39936
	global_load_lds_dwordx4 v178, s[46:47]
	s_mov_b32 m0, s36
	s_nop 0
	global_load_lds_dwordx4 v180, s[46:47]
	s_waitcnt vmcnt(8) lgkmcnt(0)
	s_setprio 1
	s_barrier
	v_mfma_f32_16x16x32_bf16 v[126:129], v[130:133], v[162:165], v[126:129]
	v_mfma_f32_16x16x32_bf16 v[122:125], v[138:141], v[162:165], v[122:125]
	v_mfma_f32_16x16x32_bf16 v[110:113], v[130:133], v[170:173], v[110:113]
	v_mfma_f32_16x16x32_bf16 v[106:109], v[138:141], v[170:173], v[106:109]
	v_mfma_f32_16x16x32_bf16 v[94:97], v[130:133], v[188:191], v[94:97]
	v_mfma_f32_16x16x32_bf16 v[90:93], v[138:141], v[188:191], v[90:93]
	v_mfma_f32_16x16x32_bf16 v[78:81], v[130:133], v[204:207], v[78:81]
	v_mfma_f32_16x16x32_bf16 v[74:77], v[138:141], v[204:207], v[74:77]
	v_mfma_f32_16x16x32_bf16 v[126:129], v[134:137], v[166:169], v[126:129]
	v_mfma_f32_16x16x32_bf16 v[122:125], v[142:145], v[166:169], v[122:125]
	v_mfma_f32_16x16x32_bf16 v[110:113], v[134:137], v[174:177], v[110:113]
	v_mfma_f32_16x16x32_bf16 v[106:109], v[142:145], v[174:177], v[106:109]
	v_mfma_f32_16x16x32_bf16 v[94:97], v[134:137], v[192:195], v[94:97]
	v_mfma_f32_16x16x32_bf16 v[90:93], v[142:145], v[192:195], v[90:93]
	v_mfma_f32_16x16x32_bf16 v[78:81], v[134:137], v[216:219], v[78:81]
	v_mfma_f32_16x16x32_bf16 v[74:77], v[142:145], v[216:219], v[74:77]
	s_setprio 0
	s_setprio 1
	v_mfma_f32_16x16x32_bf16 v[118:121], v[146:149], v[162:165], v[118:121]
	v_mfma_f32_16x16x32_bf16 v[114:117], v[154:157], v[162:165], v[114:117]
	v_mfma_f32_16x16x32_bf16 v[102:105], v[146:149], v[170:173], v[102:105]
	v_mfma_f32_16x16x32_bf16 v[98:101], v[154:157], v[170:173], v[98:101]
	v_mfma_f32_16x16x32_bf16 v[86:89], v[146:149], v[188:191], v[86:89]
	v_mfma_f32_16x16x32_bf16 v[82:85], v[154:157], v[188:191], v[82:85]
	v_mfma_f32_16x16x32_bf16 v[70:73], v[146:149], v[204:207], v[70:73]
	v_mfma_f32_16x16x32_bf16 v[66:69], v[154:157], v[204:207], v[66:69]
	v_mfma_f32_16x16x32_bf16 v[118:121], v[150:153], v[166:169], v[118:121]
	v_mfma_f32_16x16x32_bf16 v[114:117], v[158:161], v[166:169], v[114:117]
	v_mfma_f32_16x16x32_bf16 v[102:105], v[150:153], v[174:177], v[102:105]
	v_mfma_f32_16x16x32_bf16 v[98:101], v[158:161], v[174:177], v[98:101]
	v_mfma_f32_16x16x32_bf16 v[86:89], v[150:153], v[192:195], v[86:89]
	v_mfma_f32_16x16x32_bf16 v[82:85], v[158:161], v[192:195], v[82:85]
	v_mfma_f32_16x16x32_bf16 v[70:73], v[150:153], v[216:219], v[70:73]
	v_mfma_f32_16x16x32_bf16 v[66:69], v[158:161], v[216:219], v[66:69]
	s_barrier
	s_setprio 0
	s_add_i32 s29, s29, s15
	s_mov_b32 m0, s29
	ds_read_b128 v[162:165], v214 offset:49152
	ds_read_b128 v[166:169], v214 offset:50176
	ds_read_b128 v[170:173], v214 offset:51200
	ds_read_b128 v[174:177], v214 offset:52224
	ds_read_b128 v[188:191], v214 offset:53248
	ds_read_b128 v[192:195], v214 offset:54272
	ds_read_b128 v[204:207], v214 offset:55296
	ds_read_b128 v[216:219], v214 offset:56320
	global_load_lds_dwordx4 v221, s[66:67]
	s_add_i32 m0, s29, 0x2000
	s_add_u32 s46, s66, 0xb0080
	s_addc_u32 s47, s67, 0
	s_add_i32 s29, s48, s15
	global_load_lds_dwordx4 v223, s[66:67]
	s_mov_b32 m0, s29
	s_nop 0
	global_load_lds_dwordx4 v0, s[46:47]
	s_add_i32 m0, s29, 0x2000
	s_nop 0
	global_load_lds_dwordx4 v182, s[46:47]
	s_mov_b32 m0, s37
	s_nop 0
	global_load_lds_dwordx4 v225, s[72:73]
	s_mov_b32 m0, s38
	s_nop 0
	global_load_lds_dwordx4 v227, s[72:73]
	s_waitcnt vmcnt(8) lgkmcnt(0)
	s_setprio 1
	s_barrier
	v_mfma_f32_16x16x32_bf16 v[62:65], v[130:133], v[162:165], v[62:65]
	v_mfma_f32_16x16x32_bf16 v[58:61], v[138:141], v[162:165], v[58:61]
	v_mfma_f32_16x16x32_bf16 v[46:49], v[130:133], v[170:173], v[46:49]
	v_mfma_f32_16x16x32_bf16 v[42:45], v[138:141], v[170:173], v[42:45]
	v_mfma_f32_16x16x32_bf16 v[30:33], v[130:133], v[188:191], v[30:33]
	v_mfma_f32_16x16x32_bf16 v[26:29], v[138:141], v[188:191], v[26:29]
	v_mfma_f32_16x16x32_bf16 v[14:17], v[130:133], v[204:207], v[14:17]
	v_mfma_f32_16x16x32_bf16 v[10:13], v[138:141], v[204:207], v[10:13]
	v_mfma_f32_16x16x32_bf16 v[62:65], v[134:137], v[166:169], v[62:65]
	v_mfma_f32_16x16x32_bf16 v[58:61], v[142:145], v[166:169], v[58:61]
	v_mfma_f32_16x16x32_bf16 v[46:49], v[134:137], v[174:177], v[46:49]
	v_mfma_f32_16x16x32_bf16 v[42:45], v[142:145], v[174:177], v[42:45]
	v_mfma_f32_16x16x32_bf16 v[30:33], v[134:137], v[192:195], v[30:33]
	v_mfma_f32_16x16x32_bf16 v[26:29], v[142:145], v[192:195], v[26:29]
	v_mfma_f32_16x16x32_bf16 v[14:17], v[134:137], v[216:219], v[14:17]
	v_mfma_f32_16x16x32_bf16 v[10:13], v[142:145], v[216:219], v[10:13]
	s_setprio 0
	s_setprio 1
	v_mfma_f32_16x16x32_bf16 v[54:57], v[146:149], v[162:165], v[54:57]
	v_mfma_f32_16x16x32_bf16 v[50:53], v[154:157], v[162:165], v[50:53]
	v_mfma_f32_16x16x32_bf16 v[38:41], v[146:149], v[170:173], v[38:41]
	v_mfma_f32_16x16x32_bf16 v[34:37], v[154:157], v[170:173], v[34:37]
	v_mfma_f32_16x16x32_bf16 v[22:25], v[146:149], v[188:191], v[22:25]
	v_mfma_f32_16x16x32_bf16 v[18:21], v[154:157], v[188:191], v[18:21]
	v_mfma_f32_16x16x32_bf16 v[6:9], v[146:149], v[204:207], v[6:9]
	v_mfma_f32_16x16x32_bf16 v[2:5], v[154:157], v[204:207], v[2:5]
	v_mfma_f32_16x16x32_bf16 v[54:57], v[150:153], v[166:169], v[54:57]
	v_mfma_f32_16x16x32_bf16 v[50:53], v[158:161], v[166:169], v[50:53]
	v_mfma_f32_16x16x32_bf16 v[38:41], v[150:153], v[174:177], v[38:41]
	v_mfma_f32_16x16x32_bf16 v[34:37], v[158:161], v[174:177], v[34:37]
	v_mfma_f32_16x16x32_bf16 v[22:25], v[150:153], v[192:195], v[22:25]
	v_mfma_f32_16x16x32_bf16 v[18:21], v[158:161], v[192:195], v[18:21]
	v_mfma_f32_16x16x32_bf16 v[6:9], v[150:153], v[216:219], v[6:9]
	v_mfma_f32_16x16x32_bf16 v[2:5], v[158:161], v[216:219], v[2:5]
	s_barrier
	s_setprio 0
	s_add_i32 s45, s45, 2
	s_add_u32 s31, s31, 0x100
	s_addc_u32 s44, s44, 0
	s_cmp_gt_u32 s45, 41
	s_mov_b64 s[62:63], s[20:21]
	s_cbranch_scc0 .LBB0_598
	s_and_b64 vcc, exec, s[58:59]
	s_cbranch_vccz .LBB0_601
	s_barrier

; #define PG8_STAGE(bufoff, gbase, voff) do { _Pragma("unroll") for (int _i = 0; _i < 2; ++_i) \
;         __builtin_amdgcn_global_load_lds((const gunsigned*)((const gchar*)(gbase) + (voff)[_i]), (LAS unsigned*)(lds + (bufoff) + ldsw + _i * 8192), 16, 0, 0); } while (0)
; #define PG8_LDA(dst, b, h) do { _Pragma("unroll") for (int m = 0; m < 4; ++m) _Pragma("unroll") for (int k = 0; k < 2; ++k) dst[m][k] = *(const LAS bf16x8*)(lds + PG8_SA(b, h) + aoff + m * 2048 + k * 1024); } while (0)
; #define PG8_LDB(dst, b, h) do { _Pragma("unroll") for (int n = 0; n < 2; ++n) _Pragma("unroll") for (int k = 0; k < 2; ++k) dst[n][k] = *(const LAS bf16x8*)(lds + PG8_SB(b, h) + boff + n * 2048 + k * 1024); } while (0)
; #define PG8_MMA(ai, bj, At, Bt) do { __builtin_amdgcn_s_setprio(1); _Pragma("unroll") for (int m = 0; m < 4; ++m) _Pragma("unroll") for (int n = 0; n < 2; ++n) _Pragma("unroll") for (int k = 0; k < 2; ++k) \
;         acc[ai][bj][m][n] = __builtin_amdgcn_mfma_f32_16x16x32_bf16(Bt[n][k], At[m][k], acc[ai][bj][m][n], 0, 0, 0); __builtin_amdgcn_s_setprio(0); } while (0)
; #define PG8_WAIT_V(n) asm volatile("s_waitcnt vmcnt(" #n ")" ::: "memory")
; #define PG8_WAIT_L(n) asm volatile("s_waitcnt lgkmcnt(" #n ")" ::: "memory")
; #define PG8_BAR __builtin_amdgcn_s_barrier()
; #define PG8_SCHED __builtin_amdgcn_sched_barrier(0)
; template <class Epi, class Sched>
; __device__ __forceinline__ void gemm_phase(LAS unsigned char* lds, const int tid, const Gemm g, const Sched& S, const Epi& E) {
;     ...
;         for (int t = 0; t < nt; t += 2) {
;             const bool last = (t == nt - 2);
;             const gchar* a1 = cA + (size_t)(t + 1) * kstep;
;             const gchar* a2 = last ? nA : cA + (size_t)(t + 2) * kstep; const gchar* b2 = last ? nB : cB + (size_t)(t + 2) * kstep;
;             const gchar* a3 = a2 + kstep; const gchar* b3 = b2 + kstep;
;             PG8_LDB(B0, 0, 0); PG8_LDB(B1, 0, 1); PG8_SCHED; PG8_LDA(At, 0, 0); PG8_STAGE(PG8_SA(1, 1), a1 + hstep, voffA);
;             PG8_WAIT_V(8); PG8_WAIT_L(0); PG8_BAR; PG8_MMA(0, 0, At, B0); PG8_MMA(0, 1, At, B1); PG8_BAR; PG8_SCHED;
;             PG8_LDA(At, 0, 1); PG8_STAGE(PG8_SB(0, 0), b2, voffB); PG8_STAGE(PG8_SB(0, 1), b2 + hstep, voffB); PG8_STAGE(PG8_SA(0, 0), a2, voffA);
;             PG8_WAIT_V(8); PG8_WAIT_L(0); PG8_BAR; PG8_MMA(1, 0, At, B0); PG8_MMA(1, 1, At, B1); PG8_BAR; PG8_SCHED;
.LBB0_647:
	s_add_u32 s20, s58, 0xfffc0080
	s_addc_u32 s21, s59, -1
	s_add_i32 s42, 0, 0x10000
	s_cmp_eq_u32 s41, 12
	s_cselect_b32 s61, s9, s21
	s_cselect_b32 s60, s37, s20
	v_add_u32_e32 v140, s42, v143
	s_cselect_b32 s21, s7, s40
	s_cselect_b32 s20, s38, s39
	s_add_i32 s44, 0, 0x14000
	ds_read_b128 v[146:149], v140
	ds_read_b128 v[150:153], v140 offset:1024
	ds_read_b128 v[154:157], v140 offset:2048
	ds_read_b128 v[158:161], v140 offset:3072
	v_add_u32_e32 v140, s44, v143
	ds_read_b128 v[162:165], v140
	ds_read_b128 v[166:169], v140 offset:1024
	ds_read_b128 v[170:173], v140 offset:2048
	ds_read_b128 v[174:177], v140 offset:3072
	s_add_i32 m0, s23, 0xc000
	ds_read_b128 v[178:181], v145
	ds_read_b128 v[182:185], v145 offset:1024
	ds_read_b128 v[186:189], v145 offset:2048
	ds_read_b128 v[190:193], v145 offset:3072
	ds_read_b128 v[204:207], v145 offset:4096
	ds_read_b128 v[208:211], v145 offset:5120
	ds_read_b128 v[212:215], v145 offset:6144
	ds_read_b128 v[216:219], v145 offset:7168
	global_load_lds_dwordx4 v138, s[58:59]
	s_add_i32 m0, s23, 0xe000
	s_nop 0
	global_load_lds_dwordx4 v136, s[58:59]
	s_waitcnt vmcnt(8) lgkmcnt(0)
	s_setprio 1
	s_barrier
	v_mfma_f32_16x16x32_bf16 v[126:129], v[146:149], v[178:181], v[126:129]
	v_mfma_f32_16x16x32_bf16 v[122:125], v[154:157], v[178:181], v[122:125]
	v_mfma_f32_16x16x32_bf16 v[110:113], v[146:149], v[186:189], v[110:113]
	v_mfma_f32_16x16x32_bf16 v[106:109], v[154:157], v[186:189], v[106:109]
	v_mfma_f32_16x16x32_bf16 v[94:97], v[146:149], v[204:207], v[94:97]
	v_mfma_f32_16x16x32_bf16 v[90:93], v[154:157], v[204:207], v[90:93]
	v_mfma_f32_16x16x32_bf16 v[78:81], v[146:149], v[212:215], v[78:81]
	v_mfma_f32_16x16x32_bf16 v[74:77], v[154:157], v[212:215], v[74:77]
	v_mfma_f32_16x16x32_bf16 v[126:129], v[150:153], v[182:185], v[126:129]
	v_mfma_f32_16x16x32_bf16 v[122:125], v[158:161], v[182:185], v[122:125]
	v_mfma_f32_16x16x32_bf16 v[110:113], v[150:153], v[190:193], v[110:113]
	v_mfma_f32_16x16x32_bf16 v[106:109], v[158:161], v[190:193], v[106:109]
	v_mfma_f32_16x16x32_bf16 v[94:97], v[150:153], v[208:211], v[94:97]
	v_mfma_f32_16x16x32_bf16 v[90:93], v[158:161], v[208:211], v[90:93]
	v_mfma_f32_16x16x32_bf16 v[78:81], v[150:153], v[216:219], v[78:81]
	v_mfma_f32_16x16x32_bf16 v[74:77], v[158:161], v[216:219], v[74:77]
	s_setprio 0
	s_setprio 1
	v_mfma_f32_16x16x32_bf16 v[118:121], v[162:165], v[178:181], v[118:121]
	v_mfma_f32_16x16x32_bf16 v[114:117], v[170:173], v[178:181], v[114:117]
	v_mfma_f32_16x16x32_bf16 v[102:105], v[162:165], v[186:189], v[102:105]
	v_mfma_f32_16x16x32_bf16 v[98:101], v[170:173], v[186:189], v[98:101]
	v_mfma_f32_16x16x32_bf16 v[86:89], v[162:165], v[204:207], v[86:89]
	v_mfma_f32_16x16x32_bf16 v[82:85], v[170:173], v[204:207], v[82:85]
	v_mfma_f32_16x16x32_bf16 v[70:73], v[162:165], v[212:215], v[70:73]
	v_mfma_f32_16x16x32_bf16 v[66:69], v[170:173], v[212:215], v[66:69]
	v_mfma_f32_16x16x32_bf16 v[118:121], v[166:169], v[182:185], v[118:121]
	v_mfma_f32_16x16x32_bf16 v[114:117], v[174:177], v[182:185], v[114:117]
	v_mfma_f32_16x16x32_bf16 v[102:105], v[166:169], v[190:193], v[102:105]
	v_mfma_f32_16x16x32_bf16 v[98:101], v[174:177], v[190:193], v[98:101]
	v_mfma_f32_16x16x32_bf16 v[86:89], v[166:169], v[208:211], v[86:89]
	v_mfma_f32_16x16x32_bf16 v[82:85], v[174:177], v[208:211], v[82:85]
	v_mfma_f32_16x16x32_bf16 v[70:73], v[166:169], v[216:219], v[70:73]
	v_mfma_f32_16x16x32_bf16 v[66:69], v[174:177], v[216:219], v[66:69]
	s_barrier
	s_setprio 0
	s_add_i32 s42, s42, s12
	s_mov_b32 m0, s42
	ds_read_b128 v[178:181], v145 offset:16384
	ds_read_b128 v[182:185], v145 offset:17408
	ds_read_b128 v[186:189], v145 offset:18432
	ds_read_b128 v[190:193], v145 offset:19456
	ds_read_b128 v[204:207], v145 offset:20480
	ds_read_b128 v[208:211], v145 offset:21504
	ds_read_b128 v[212:215], v145 offset:22528
	ds_read_b128 v[216:219], v145 offset:23552
	global_load_lds_dwordx4 v0, s[20:21]
	s_add_i32 m0, s42, 0x2000
	s_add_u32 s42, s20, 0x40000
	s_addc_u32 s43, s21, 0
	s_add_i32 s44, s44, s12
	global_load_lds_dwordx4 v130, s[20:21]
	s_mov_b32 m0, s44
	s_nop 0
	global_load_lds_dwordx4 v0, s[42:43]
	s_add_i32 m0, s44, 0x2000
	s_nop 0
	global_load_lds_dwordx4 v130, s[42:43]
	s_mov_b32 m0, s23
	s_nop 0
	global_load_lds_dwordx4 v134, s[60:61]
	s_mov_b32 m0, s24
	s_nop 0
	global_load_lds_dwordx4 v132, s[60:61]
	s_waitcnt vmcnt(8) lgkmcnt(0)
	s_setprio 1
	s_barrier
	v_mfma_f32_16x16x32_bf16 v[62:65], v[146:149], v[178:181], v[62:65]
	v_mfma_f32_16x16x32_bf16 v[58:61], v[154:157], v[178:181], v[58:61]
	v_mfma_f32_16x16x32_bf16 v[46:49], v[146:149], v[186:189], v[46:49]
	v_mfma_f32_16x16x32_bf16 v[42:45], v[154:157], v[186:189], v[42:45]
	v_mfma_f32_16x16x32_bf16 v[30:33], v[146:149], v[204:207], v[30:33]
	v_mfma_f32_16x16x32_bf16 v[26:29], v[154:157], v[204:207], v[26:29]
	v_mfma_f32_16x16x32_bf16 v[14:17], v[146:149], v[212:215], v[14:17]
	v_mfma_f32_16x16x32_bf16 v[10:13], v[154:157], v[212:215], v[10:13]
	v_mfma_f32_16x16x32_bf16 v[62:65], v[150:153], v[182:185], v[62:65]
	v_mfma_f32_16x16x32_bf16 v[58:61], v[158:161], v[182:185], v[58:61]
	v_mfma_f32_16x16x32_bf16 v[46:49], v[150:153], v[190:193], v[46:49]
	v_mfma_f32_16x16x32_bf16 v[42:45], v[158:161], v[190:193], v[42:45]
	v_mfma_f32_16x16x32_bf16 v[30:33], v[150:153], v[208:211], v[30:33]
	v_mfma_f32_16x16x32_bf16 v[26:29], v[158:161], v[208:211], v[26:29]
	v_mfma_f32_16x16x32_bf16 v[14:17], v[150:153], v[216:219], v[14:17]
	v_mfma_f32_16x16x32_bf16 v[10:13], v[158:161], v[216:219], v[10:13]
	s_setprio 0
	s_setprio 1
	v_mfma_f32_16x16x32_bf16 v[54:57], v[162:165], v[178:181], v[54:57]
	v_mfma_f32_16x16x32_bf16 v[50:53], v[170:173], v[178:181], v[50:53]
	v_mfma_f32_16x16x32_bf16 v[38:41], v[162:165], v[186:189], v[38:41]
	v_mfma_f32_16x16x32_bf16 v[34:37], v[170:173], v[186:189], v[34:37]
	v_mfma_f32_16x16x32_bf16 v[22:25], v[162:165], v[204:207], v[22:25]
	v_mfma_f32_16x16x32_bf16 v[18:21], v[170:173], v[204:207], v[18:21]
	v_mfma_f32_16x16x32_bf16 v[6:9], v[162:165], v[212:215], v[6:9]
	v_mfma_f32_16x16x32_bf16 v[2:5], v[170:173], v[212:215], v[2:5]
	v_mfma_f32_16x16x32_bf16 v[54:57], v[166:169], v[182:185], v[54:57]
	v_mfma_f32_16x16x32_bf16 v[50:53], v[174:177], v[182:185], v[50:53]
	v_mfma_f32_16x16x32_bf16 v[38:41], v[166:169], v[190:193], v[38:41]
	v_mfma_f32_16x16x32_bf16 v[34:37], v[174:177], v[190:193], v[34:37]
	v_mfma_f32_16x16x32_bf16 v[22:25], v[166:169], v[208:211], v[22:25]
	v_mfma_f32_16x16x32_bf16 v[18:21], v[174:177], v[208:211], v[18:21]
	v_mfma_f32_16x16x32_bf16 v[6:9], v[166:169], v[216:219], v[6:9]
	v_mfma_f32_16x16x32_bf16 v[2:5], v[174:177], v[216:219], v[2:5]
	s_barrier
; #define PG8_STAGE(bufoff, gbase, voff) do { _Pragma("unroll") for (int _i = 0; _i < 2; ++_i) \
;         __builtin_amdgcn_global_load_lds((const gunsigned*)((const gchar*)(gbase) + (voff)[_i]), (LAS unsigned*)(lds + (bufoff) + ldsw + _i * 8192), 16, 0, 0); } while (0)
; #define PG8_LDA(dst, b, h) do { _Pragma("unroll") for (int m = 0; m < 4; ++m) _Pragma("unroll") for (int k = 0; k < 2; ++k) dst[m][k] = *(const LAS bf16x8*)(lds + PG8_SA(b, h) + aoff + m * 2048 + k * 1024); } while (0)
; #define PG8_LDB(dst, b, h) do { _Pragma("unroll") for (int n = 0; n < 2; ++n) _Pragma("unroll") for (int k = 0; k < 2; ++k) dst[n][k] = *(const LAS bf16x8*)(lds + PG8_SB(b, h) + boff + n * 2048 + k * 1024); } while (0)
; #define PG8_MMA(ai, bj, At, Bt) do { __builtin_amdgcn_s_setprio(1); _Pragma("unroll") for (int m = 0; m < 4; ++m) _Pragma("unroll") for (int n = 0; n < 2; ++n) _Pragma("unroll") for (int k = 0; k < 2; ++k) \
;         acc[ai][bj][m][n] = __builtin_amdgcn_mfma_f32_16x16x32_bf16(Bt[n][k], At[m][k], acc[ai][bj][m][n], 0, 0, 0); __builtin_amdgcn_s_setprio(0); } while (0)
; #define PG8_WAIT_V(n) asm volatile("s_waitcnt vmcnt(" #n ")" ::: "memory")
; #define PG8_WAIT_L(n) asm volatile("s_waitcnt lgkmcnt(" #n ")" ::: "memory")
; #define PG8_BAR __builtin_amdgcn_s_barrier()
; #define PG8_SCHED __builtin_amdgcn_sched_barrier(0)
; template <class Epi, class Sched>
; __device__ __forceinline__ void gemm_phase(LAS unsigned char* lds, const int tid, const Gemm g, const Sched& S, const Epi& E) {
;     ...
;             PG8_LDB(B0, 1, 0); PG8_LDB(B1, 1, 1); PG8_SCHED; PG8_LDA(At, 1, 0); PG8_STAGE(PG8_SA(0, 1), a2 + hstep, voffA);
;             PG8_WAIT_V(8); PG8_WAIT_L(0); PG8_BAR; PG8_MMA(0, 0, At, B0); PG8_MMA(0, 1, At, B1); PG8_BAR; PG8_SCHED;
;             PG8_LDA(At, 1, 1); PG8_STAGE(PG8_SB(1, 0), b3, voffB); PG8_STAGE(PG8_SB(1, 1), b3 + hstep, voffB); PG8_STAGE(PG8_SA(1, 0), a3, voffA);
;             PG8_WAIT_V(8); PG8_WAIT_L(0); PG8_BAR; PG8_MMA(1, 0, At, B0); PG8_MMA(1, 1, At, B1); PG8_BAR; PG8_SCHED;
;         }
;         if (wr == 0) PG8_BAR;
	s_setprio 0
	s_add_i32 s44, 0, 0x18000
	s_add_i32 s45, 0, 0x1c000
	v_add_u32_e32 v158, s44, v143
	v_add_u32_e32 v174, s45, v143
	ds_read_b128 v[146:149], v158
	ds_read_b128 v[150:153], v158 offset:1024
	ds_read_b128 v[154:157], v158 offset:2048
	ds_read_b128 v[158:161], v158 offset:3072
	ds_read_b128 v[162:165], v174
	ds_read_b128 v[166:169], v174 offset:1024
	ds_read_b128 v[170:173], v174 offset:2048
	ds_read_b128 v[174:177], v174 offset:3072
	s_add_u32 s42, s60, 0x40000
	s_addc_u32 s43, s61, 0
	s_mov_b32 m0, s29
	ds_read_b128 v[178:181], v145 offset:32768
	ds_read_b128 v[182:185], v145 offset:33792
	ds_read_b128 v[186:189], v145 offset:34816
	ds_read_b128 v[190:193], v145 offset:35840
	ds_read_b128 v[204:207], v145 offset:36864
	ds_read_b128 v[208:211], v145 offset:37888
	ds_read_b128 v[212:215], v145 offset:38912
	ds_read_b128 v[216:219], v145 offset:39936
	global_load_lds_dwordx4 v134, s[42:43]
	s_mov_b32 m0, s30
	s_nop 0
	global_load_lds_dwordx4 v132, s[42:43]
	s_waitcnt vmcnt(8) lgkmcnt(0)
	s_setprio 1
	s_barrier
	v_mfma_f32_16x16x32_bf16 v[126:129], v[146:149], v[178:181], v[126:129]
	v_mfma_f32_16x16x32_bf16 v[122:125], v[154:157], v[178:181], v[122:125]
	v_mfma_f32_16x16x32_bf16 v[110:113], v[146:149], v[186:189], v[110:113]
	v_mfma_f32_16x16x32_bf16 v[106:109], v[154:157], v[186:189], v[106:109]
	v_mfma_f32_16x16x32_bf16 v[94:97], v[146:149], v[204:207], v[94:97]
	v_mfma_f32_16x16x32_bf16 v[90:93], v[154:157], v[204:207], v[90:93]
	v_mfma_f32_16x16x32_bf16 v[78:81], v[146:149], v[212:215], v[78:81]
	v_mfma_f32_16x16x32_bf16 v[74:77], v[154:157], v[212:215], v[74:77]
	v_mfma_f32_16x16x32_bf16 v[126:129], v[150:153], v[182:185], v[126:129]
	v_mfma_f32_16x16x32_bf16 v[122:125], v[158:161], v[182:185], v[122:125]
	v_mfma_f32_16x16x32_bf16 v[110:113], v[150:153], v[190:193], v[110:113]
	v_mfma_f32_16x16x32_bf16 v[106:109], v[158:161], v[190:193], v[106:109]
	v_mfma_f32_16x16x32_bf16 v[94:97], v[150:153], v[208:211], v[94:97]
	v_mfma_f32_16x16x32_bf16 v[90:93], v[158:161], v[208:211], v[90:93]
	v_mfma_f32_16x16x32_bf16 v[78:81], v[150:153], v[216:219], v[78:81]
	v_mfma_f32_16x16x32_bf16 v[74:77], v[158:161], v[216:219], v[74:77]
	s_setprio 0
	s_setprio 1
	v_mfma_f32_16x16x32_bf16 v[118:121], v[162:165], v[178:181], v[118:121]
	v_mfma_f32_16x16x32_bf16 v[114:117], v[170:173], v[178:181], v[114:117]
	v_mfma_f32_16x16x32_bf16 v[102:105], v[162:165], v[186:189], v[102:105]
	v_mfma_f32_16x16x32_bf16 v[98:101], v[170:173], v[186:189], v[98:101]
	v_mfma_f32_16x16x32_bf16 v[86:89], v[162:165], v[204:207], v[86:89]
	v_mfma_f32_16x16x32_bf16 v[82:85], v[170:173], v[204:207], v[82:85]
	v_mfma_f32_16x16x32_bf16 v[70:73], v[162:165], v[212:215], v[70:73]
	v_mfma_f32_16x16x32_bf16 v[66:69], v[170:173], v[212:215], v[66:69]
	v_mfma_f32_16x16x32_bf16 v[118:121], v[166:169], v[182:185], v[118:121]
	v_mfma_f32_16x16x32_bf16 v[114:117], v[174:177], v[182:185], v[114:117]
	v_mfma_f32_16x16x32_bf16 v[102:105], v[166:169], v[190:193], v[102:105]
	v_mfma_f32_16x16x32_bf16 v[98:101], v[174:177], v[190:193], v[98:101]
	v_mfma_f32_16x16x32_bf16 v[86:89], v[166:169], v[208:211], v[86:89]
	v_mfma_f32_16x16x32_bf16 v[82:85], v[174:177], v[208:211], v[82:85]
	v_mfma_f32_16x16x32_bf16 v[70:73], v[166:169], v[216:219], v[70:73]
	v_mfma_f32_16x16x32_bf16 v[66:69], v[174:177], v[216:219], v[66:69]
	s_barrier
	s_setprio 0
	s_add_i32 s42, s44, s12
	s_mov_b32 m0, s42
	ds_read_b128 v[178:181], v145 offset:49152
	ds_read_b128 v[182:185], v145 offset:50176
	ds_read_b128 v[186:189], v145 offset:51200
	ds_read_b128 v[190:193], v145 offset:52224
	ds_read_b128 v[204:207], v145 offset:53248
	ds_read_b128 v[208:211], v145 offset:54272
	ds_read_b128 v[212:215], v145 offset:55296
	ds_read_b128 v[216:219], v145 offset:56320
	global_load_lds_dwordx4 v141, s[20:21]
	s_add_i32 m0, s42, 0x2000
	s_add_i32 s42, s45, s12
	global_load_lds_dwordx4 v195, s[20:21]
	s_add_u32 s20, s20, 0x40080
	s_addc_u32 s21, s21, 0
	s_mov_b32 m0, s42
	s_nop 0
	global_load_lds_dwordx4 v0, s[20:21]
	s_add_i32 m0, s42, 0x2000
	s_nop 0
	global_load_lds_dwordx4 v130, s[20:21]
	s_mov_b32 m0, s31
	s_nop 0
	global_load_lds_dwordx4 v221, s[60:61]
	s_mov_b32 m0, s34
	s_nop 0
	global_load_lds_dwordx4 v223, s[60:61]
	s_waitcnt vmcnt(8) lgkmcnt(0)
	s_setprio 1
	s_barrier
	v_mfma_f32_16x16x32_bf16 v[62:65], v[146:149], v[178:181], v[62:65]
	v_mfma_f32_16x16x32_bf16 v[58:61], v[154:157], v[178:181], v[58:61]
	v_mfma_f32_16x16x32_bf16 v[46:49], v[146:149], v[186:189], v[46:49]
	v_mfma_f32_16x16x32_bf16 v[42:45], v[154:157], v[186:189], v[42:45]
	v_mfma_f32_16x16x32_bf16 v[30:33], v[146:149], v[204:207], v[30:33]
	v_mfma_f32_16x16x32_bf16 v[26:29], v[154:157], v[204:207], v[26:29]
	v_mfma_f32_16x16x32_bf16 v[14:17], v[146:149], v[212:215], v[14:17]
	v_mfma_f32_16x16x32_bf16 v[10:13], v[154:157], v[212:215], v[10:13]
	v_mfma_f32_16x16x32_bf16 v[62:65], v[150:153], v[182:185], v[62:65]
	v_mfma_f32_16x16x32_bf16 v[58:61], v[158:161], v[182:185], v[58:61]
	v_mfma_f32_16x16x32_bf16 v[46:49], v[150:153], v[190:193], v[46:49]
	v_mfma_f32_16x16x32_bf16 v[42:45], v[158:161], v[190:193], v[42:45]
	v_mfma_f32_16x16x32_bf16 v[30:33], v[150:153], v[208:211], v[30:33]
	v_mfma_f32_16x16x32_bf16 v[26:29], v[158:161], v[208:211], v[26:29]
	v_mfma_f32_16x16x32_bf16 v[14:17], v[150:153], v[216:219], v[14:17]
	v_mfma_f32_16x16x32_bf16 v[10:13], v[158:161], v[216:219], v[10:13]
	s_setprio 0
	s_setprio 1
	v_mfma_f32_16x16x32_bf16 v[54:57], v[162:165], v[178:181], v[54:57]
	v_mfma_f32_16x16x32_bf16 v[50:53], v[170:173], v[178:181], v[50:53]
	v_mfma_f32_16x16x32_bf16 v[38:41], v[162:165], v[186:189], v[38:41]
	v_mfma_f32_16x16x32_bf16 v[34:37], v[170:173], v[186:189], v[34:37]
	v_mfma_f32_16x16x32_bf16 v[22:25], v[162:165], v[204:207], v[22:25]
	v_mfma_f32_16x16x32_bf16 v[18:21], v[170:173], v[204:207], v[18:21]
	v_mfma_f32_16x16x32_bf16 v[6:9], v[162:165], v[212:215], v[6:9]
	v_mfma_f32_16x16x32_bf16 v[2:5], v[170:173], v[212:215], v[2:5]
	v_mfma_f32_16x16x32_bf16 v[54:57], v[166:169], v[182:185], v[54:57]
	v_mfma_f32_16x16x32_bf16 v[50:53], v[174:177], v[182:185], v[50:53]
	v_mfma_f32_16x16x32_bf16 v[38:41], v[166:169], v[190:193], v[38:41]
	v_mfma_f32_16x16x32_bf16 v[34:37], v[174:177], v[190:193], v[34:37]
	v_mfma_f32_16x16x32_bf16 v[22:25], v[166:169], v[208:211], v[22:25]
	v_mfma_f32_16x16x32_bf16 v[18:21], v[174:177], v[208:211], v[18:21]
	v_mfma_f32_16x16x32_bf16 v[6:9], v[166:169], v[216:219], v[6:9]
	v_mfma_f32_16x16x32_bf16 v[2:5], v[174:177], v[216:219], v[2:5]
	s_barrier
	s_setprio 0
	s_add_i32 s41, s41, 2
	s_add_u32 s39, s39, 0x100
	s_addc_u32 s40, s40, 0
	s_add_u32 s58, s58, 0x100
	s_addc_u32 s59, s59, 0
	s_cmp_gt_u32 s41, 13
	s_cbranch_scc0 .LBB0_647
	s_and_b64 vcc, exec, s[4:5]
	s_cbranch_vccz .LBB0_650
	s_barrier
